# attention steps: canonicalising v_max pairs before the row-max combine removed, zero-initialised probability-sum pk_add folded
# speedup vs baseline: 1.0060x; 1.0004x over previous
.LBB0_106:
	s_and_b32 s4, s3, 0x4000
	s_add_i32 s45, s4, 0
	v_add_u32_e32 v50, s45, v133
	v_add_u32_e32 v51, v50, v134
	s_waitcnt vmcnt(1)
	ds_write_b128 v51, v[106:109] offset:49152
	v_add3_u32 v51, v50, v135, v136
	v_add3_u32 v50, v50, v137, v136
	s_waitcnt vmcnt(0)
	ds_write_b64 v51, v[102:103] offset:57344
	ds_write_b64 v50, v[104:105] offset:57344
	global_load_dwordx4 v[106:109], v[130:131], off
	global_load_dwordx4 v[102:105], v[128:129], off
	s_waitcnt lgkmcnt(3)
	v_lshrrev_b32_e32 v50, s33, v142
	v_and_b32_e32 v50, 1, v50
	v_cmp_eq_u32_e64 s[38:39], 1, v50
	v_bfe_u32 v50, v142, s33, 1
	s_andn2_b64 s[4:5], s[0:1], exec
	s_and_b64 s[40:41], s[0:1], exec
	v_cmp_ne_u32_e32 vcc, 0, v50
	s_or_b64 s[4:5], s[4:5], s[40:41]
	s_waitcnt lgkmcnt(0)
	s_barrier
	s_cbranch_vccz .LBB0_104
	v_add_u32_e32 v50, s45, v0
	s_mov_b32 s44, 0x7f800000
	v_add_u32_e32 v146, v50, v138
	ds_read_b128 v[66:69], v146 offset:49152
	v_add_u32_e32 v147, v50, v139
	ds_read_b128 v[110:113], v147 offset:49152
	v_add_u32_e32 v144, v50, v140
	ds_read_b128 v[114:117], v144 offset:49152
	v_add_u32_e32 v145, v50, v141
	ds_read_b128 v[118:121], v145 offset:49152
	ds_read_b128 v[122:125], v146 offset:53248
	ds_read_b128 v[148:151], v147 offset:53248
	ds_read_b128 v[152:155], v144 offset:53248
	ds_read_b128 v[156:159], v145 offset:53248
	s_waitcnt lgkmcnt(7)
	v_mfma_f32_32x32x16_bf16 v[50:65], v[66:69], v[98:101], v[34:49]
	s_waitcnt lgkmcnt(6)
	v_mfma_f32_32x32x16_bf16 v[50:65], v[110:113], v[86:89], v[50:65]
	s_cmp_lg_u64 vcc, -1
	s_cselect_b64 s[40:41], -1, 0
	s_cmp_eq_u64 vcc, -1
	s_cselect_b64 s[42:43], -1, 0
	s_or_b64 vcc, s[42:43], s[38:39]
	s_waitcnt lgkmcnt(3)
	v_mfma_f32_32x32x16_bf16 v[66:81], v[122:125], v[98:101], v[34:49]
	s_waitcnt lgkmcnt(2)
	v_mfma_f32_32x32x16_bf16 v[66:81], v[148:151], v[86:89], v[66:81]
	v_mfma_f32_32x32x16_bf16 v[50:65], v[114:117], v[82:85], v[50:65]
	s_waitcnt lgkmcnt(1)
	v_mfma_f32_32x32x16_bf16 v[66:81], v[152:155], v[82:85], v[66:81]
	v_mfma_f32_32x32x16_bf16 v[50:65], v[118:121], v[90:93], v[50:65]
	ds_read_b128 v[114:117], v146 offset:57344
	ds_read_b128 v[110:113], v147 offset:57344
	ds_read_b128 v[118:121], v144 offset:57344
	ds_read_b128 v[122:125], v145 offset:57344
	s_waitcnt lgkmcnt(4)
	v_mfma_f32_32x32x16_bf16 v[66:81], v[156:159], v[90:93], v[66:81]
	s_nop 5
	v_max3_f32 v149, v50, v51, v52
	v_max3_f32 v149, v149, v53, v54
	v_max3_f32 v149, v149, v55, v56
	v_max3_f32 v149, v149, v57, v58
	v_max3_f32 v149, v149, v59, v60
	v_max3_f32 v149, v149, v61, v62
	v_max3_f32 v149, v149, v63, v64
	v_max3_f32 v150, v66, v67, v68
	v_max3_f32 v150, v150, v69, v70
	v_max3_f32 v150, v150, v71, v72
	v_max3_f32 v150, v150, v73, v74
	v_max3_f32 v150, v150, v75, v76
	v_max3_f32 v150, v150, v77, v78
	v_max3_f32 v150, v150, v79, v80
	v_max3_f32 v148, v149, v150, v65
	v_max_f32_e32 v148, v148, v81
	v_cndmask_b32_e32 v148, v225, v148, vcc
	v_mov_b32_e32 v149, v148
	s_nop 1
	v_permlane32_swap_b32_e32 v148, v149
	v_max_f32_e32 v148, v148, v149
	v_cndmask_b32_e64 v149, v227, v228, s[0:1]
	v_cmp_gt_f32_e32 vcc, v148, v149
	s_cbranch_vccz .LBB0_109
	s_nop 0
	v_cndmask_b32_e32 v36, 0, v148, vcc
	v_exp_f32_e64 v38, -v36
	v_add_f32_e32 v143, v143, v36
	v_xor_b32_e32 v34, 0x80000000, v143
	v_pk_add_f32 v[50:51], v[50:51], v[36:37] op_sel_hi:[1,0] neg_lo:[0,1] neg_hi:[0,1]
	v_mul_f32_e32 v127, v127, v38
	v_pk_add_f32 v[66:67], v[66:67], v[36:37] op_sel_hi:[1,0] neg_lo:[0,1] neg_hi:[0,1]
	v_pk_add_f32 v[52:53], v[52:53], v[36:37] op_sel_hi:[1,0] neg_lo:[0,1] neg_hi:[0,1]
	v_pk_add_f32 v[68:69], v[68:69], v[36:37] op_sel_hi:[1,0] neg_lo:[0,1] neg_hi:[0,1]
	v_pk_add_f32 v[54:55], v[54:55], v[36:37] op_sel_hi:[1,0] neg_lo:[0,1] neg_hi:[0,1]
	v_pk_add_f32 v[70:71], v[70:71], v[36:37] op_sel_hi:[1,0] neg_lo:[0,1] neg_hi:[0,1]
	v_pk_add_f32 v[56:57], v[56:57], v[36:37] op_sel_hi:[1,0] neg_lo:[0,1] neg_hi:[0,1]
	v_pk_add_f32 v[72:73], v[72:73], v[36:37] op_sel_hi:[1,0] neg_lo:[0,1] neg_hi:[0,1]
	v_pk_add_f32 v[58:59], v[58:59], v[36:37] op_sel_hi:[1,0] neg_lo:[0,1] neg_hi:[0,1]
	v_pk_add_f32 v[74:75], v[74:75], v[36:37] op_sel_hi:[1,0] neg_lo:[0,1] neg_hi:[0,1]
	v_pk_add_f32 v[60:61], v[60:61], v[36:37] op_sel_hi:[1,0] neg_lo:[0,1] neg_hi:[0,1]
	v_pk_add_f32 v[76:77], v[76:77], v[36:37] op_sel_hi:[1,0] neg_lo:[0,1] neg_hi:[0,1]
	v_pk_add_f32 v[62:63], v[62:63], v[36:37] op_sel_hi:[1,0] neg_lo:[0,1] neg_hi:[0,1]
	v_pk_add_f32 v[78:79], v[78:79], v[36:37] op_sel_hi:[1,0] neg_lo:[0,1] neg_hi:[0,1]
	v_pk_mul_f32 v[16:17], v[16:17], v[38:39] op_sel_hi:[1,0]
	v_pk_mul_f32 v[14:15], v[14:15], v[38:39] op_sel_hi:[1,0]
	v_pk_mul_f32 v[12:13], v[12:13], v[38:39] op_sel_hi:[1,0]
	v_pk_mul_f32 v[10:11], v[10:11], v[38:39] op_sel_hi:[1,0]
	v_pk_mul_f32 v[8:9], v[8:9], v[38:39] op_sel_hi:[1,0]
	v_pk_mul_f32 v[6:7], v[6:7], v[38:39] op_sel_hi:[1,0]
	v_pk_mul_f32 v[4:5], v[4:5], v[38:39] op_sel_hi:[1,0]
	v_pk_mul_f32 v[2:3], v[2:3], v[38:39] op_sel_hi:[1,0]
	v_pk_mul_f32 v[32:33], v[32:33], v[38:39] op_sel_hi:[1,0]
	v_pk_mul_f32 v[30:31], v[30:31], v[38:39] op_sel_hi:[1,0]
	v_pk_mul_f32 v[28:29], v[28:29], v[38:39] op_sel_hi:[1,0]
	v_pk_mul_f32 v[26:27], v[26:27], v[38:39] op_sel_hi:[1,0]
	v_pk_mul_f32 v[24:25], v[24:25], v[38:39] op_sel_hi:[1,0]
	v_pk_mul_f32 v[22:23], v[22:23], v[38:39] op_sel_hi:[1,0]
	v_pk_mul_f32 v[20:21], v[20:21], v[38:39] op_sel_hi:[1,0]
	v_pk_mul_f32 v[18:19], v[18:19], v[38:39] op_sel_hi:[1,0]
	v_pk_add_f32 v[64:65], v[64:65], v[36:37] op_sel_hi:[1,0] neg_lo:[0,1] neg_hi:[0,1]
	v_pk_add_f32 v[80:81], v[80:81], v[36:37] op_sel_hi:[1,0] neg_lo:[0,1] neg_hi:[0,1]
	v_mov_b32_e32 v35, v34
	v_mov_b32_e32 v36, v34
	v_mov_b32_e32 v37, v34
	v_mov_b32_e32 v38, v34
	v_mov_b32_e32 v39, v34
	v_mov_b32_e32 v40, v34
	v_mov_b32_e32 v41, v34
	v_mov_b32_e32 v42, v34
	v_mov_b32_e32 v43, v34
	v_mov_b32_e32 v44, v34
	v_mov_b32_e32 v45, v34
	v_mov_b32_e32 v46, v34
	v_mov_b32_e32 v47, v34
	v_mov_b32_e32 v48, v34
	v_mov_b32_e32 v49, v34
.LBB0_109:
	v_exp_f32_e32 v151, v50
	v_exp_f32_e32 v150, v66
	v_exp_f32_e32 v51, v51
	v_exp_f32_e32 v50, v67
	v_exp_f32_e32 v153, v52
	v_exp_f32_e32 v152, v68
	v_exp_f32_e32 v53, v53
	v_exp_f32_e32 v52, v69
	v_exp_f32_e32 v69, v54
	v_exp_f32_e32 v68, v70
	v_pk_add_f32 v[66:67], v[50:51], v[150:151]
	v_exp_f32_e32 v155, v55
	v_exp_f32_e32 v154, v71
	v_pk_add_f32 v[66:67], v[152:153], v[66:67]
	v_exp_f32_e32 v71, v56
	v_exp_f32_e32 v70, v72
	v_pk_add_f32 v[66:67], v[52:53], v[66:67]
	v_exp_f32_e32 v157, v57
	v_exp_f32_e32 v156, v73
	v_exp_f32_e32 v73, v58
	v_exp_f32_e32 v72, v74
	v_pk_add_f32 v[54:55], v[68:69], v[66:67]
	v_exp_f32_e32 v159, v59
	v_exp_f32_e32 v158, v75
	v_pk_add_f32 v[54:55], v[154:155], v[54:55]
	v_exp_f32_e32 v75, v60
	v_exp_f32_e32 v74, v76
	v_pk_add_f32 v[54:55], v[70:71], v[54:55]
	v_exp_f32_e32 v161, v61
	v_exp_f32_e32 v160, v77
	v_pk_add_f32 v[54:55], v[156:157], v[54:55]
	v_exp_f32_e32 v77, v62
	v_exp_f32_e32 v76, v78
	v_pk_add_f32 v[54:55], v[72:73], v[54:55]
	v_exp_f32_e32 v177, v63
	v_exp_f32_e32 v176, v79
	v_pk_add_f32 v[54:55], v[158:159], v[54:55]
	v_exp_f32_e32 v79, v64
	v_exp_f32_e32 v78, v80
	v_pk_add_f32 v[54:55], v[74:75], v[54:55]
	v_exp_f32_e32 v179, v65
	v_exp_f32_e32 v178, v81
	v_pk_add_f32 v[54:55], v[160:161], v[54:55]
	v_cvt_pk_bf16_f32 v58, v151, v51
	v_pk_add_f32 v[54:55], v[76:77], v[54:55]
	v_cvt_pk_bf16_f32 v59, v153, v53
	v_pk_add_f32 v[54:55], v[176:177], v[54:55]
	v_cvt_pk_bf16_f32 v60, v69, v155
	v_pk_add_f32 v[54:55], v[78:79], v[54:55]
	v_cvt_pk_bf16_f32 v61, v71, v157
	v_pk_add_f32 v[54:55], v[178:179], v[54:55]
	v_cvt_pk_bf16_f32 v62, v73, v159
	v_add_f32_e32 v66, v54, v55
	v_cvt_pk_bf16_f32 v63, v75, v161
	v_cvt_pk_bf16_f32 v64, v77, v177
	v_cvt_pk_bf16_f32 v65, v79, v179
	v_cvt_pk_bf16_f32 v54, v150, v50
	v_cvt_pk_bf16_f32 v55, v152, v52
	v_cvt_pk_bf16_f32 v56, v68, v154
	v_cvt_pk_bf16_f32 v57, v70, v156
	v_cvt_pk_bf16_f32 v50, v72, v158
	v_cvt_pk_bf16_f32 v51, v74, v160
	v_cvt_pk_bf16_f32 v52, v76, v176
	s_andn2_b64 vcc, exec, s[40:41]
	v_cvt_pk_bf16_f32 v53, v78, v178
	s_cbranch_vccnz .LBB0_111
	v_cndmask_b32_e64 v66, 0, v66, s[38:39]
	v_cndmask_b32_e64 v58, 0, v58, s[38:39]
	v_cndmask_b32_e64 v59, 0, v59, s[38:39]
	v_cndmask_b32_e64 v60, 0, v60, s[38:39]
	v_cndmask_b32_e64 v61, 0, v61, s[38:39]
	v_cndmask_b32_e64 v62, 0, v62, s[38:39]
	v_cndmask_b32_e64 v63, 0, v63, s[38:39]
	v_cndmask_b32_e64 v64, 0, v64, s[38:39]
	v_cndmask_b32_e64 v65, 0, v65, s[38:39]
	v_cndmask_b32_e64 v54, 0, v54, s[38:39]
	v_cndmask_b32_e64 v55, 0, v55, s[38:39]
	v_cndmask_b32_e64 v56, 0, v56, s[38:39]
	v_cndmask_b32_e64 v57, 0, v57, s[38:39]
	v_cndmask_b32_e64 v50, 0, v50, s[38:39]
	v_cndmask_b32_e64 v51, 0, v51, s[38:39]
	v_cndmask_b32_e64 v52, 0, v52, s[38:39]
	v_cndmask_b32_e64 v53, 0, v53, s[38:39]

.LBB0_122:
	s_xor_b64 s[4:5], s[30:31], -1
	s_add_u32 s22, s22, s6
	s_addc_u32 s23, s23, 0
	s_add_u32 s0, s22, 0xa00000
	s_addc_u32 s1, s23, 0
	s_lshl_b32 s3, s2, 14
	s_and_b32 s3, s3, 0x4000
	v_sub_u32_e64 v122, s2, 8 clamp
	s_add_i32 s3, s3, 0
	v_add_u32_e32 v50, s3, v133
	v_lshlrev_b32_e32 v52, 7, v122
	v_mov_b32_e32 v53, v1
	v_add_u32_e32 v145, v50, v134
	v_add_u32_e32 v51, v50, v135
	v_add_u32_e32 v50, v50, v137
	v_lshl_add_u64 v[52:53], s[22:23], 0, v[52:53]
	v_add_u32_e32 v146, v51, v136
	v_add_u32_e32 v147, v50, v136
	v_lshlrev_b32_e32 v50, 13, v122
	v_mov_b32_e32 v51, v1
	v_lshl_add_u64 v[52:53], v[52:53], 0, v[196:197]
	v_mov_b32_e32 v209, v1
	v_lshl_add_u64 v[50:51], s[0:1], 0, v[50:51]
	v_lshl_add_u64 v[110:111], v[52:53], 0, v[208:209]
	s_mov_b32 s6, 0xa80000
	v_add_u32_e32 v112, s3, v0
	s_waitcnt vmcnt(1)
	ds_write_b128 v145, v[106:109] offset:49152
	s_waitcnt vmcnt(0)
	ds_write_b64 v146, v[102:103] offset:57344
	ds_write_b64 v147, v[104:105] offset:57344
	v_lshl_add_u64 v[50:51], v[194:195], 1, v[50:51]
	v_add_co_u32_e32 v52, vcc, s6, v110
	s_mov_b32 s30, 0x7f800000
	v_add_u32_e32 v130, v112, v138
	v_addc_co_u32_e32 v53, vcc, 0, v111, vcc
	global_load_dwordx4 v[106:109], v[50:51], off
	global_load_dwordx4 v[102:105], v[52:53], off
	s_waitcnt lgkmcnt(0)
	s_barrier
	ds_read_b128 v[66:69], v130 offset:49152
	ds_read_b128 v[70:73], v130 offset:53248
	v_add_u32_e32 v131, v112, v139
	s_waitcnt lgkmcnt(1)
	v_mfma_f32_32x32x16_bf16 v[50:65], v[66:69], v[98:101], v[34:49]
	v_add_u32_e32 v142, v112, v140
	v_add_u32_e32 v143, v112, v141
	s_cmpk_lt_u32 s8, 0x100
	s_cselect_b64 s[38:39], -1, 0
	v_cndmask_b32_e64 v125, v193, 0, s[38:39]
	s_and_b64 s[22:23], s[36:37], s[38:39]
	v_cmp_gt_u32_e32 vcc, v162, v125
	s_waitcnt lgkmcnt(0)
	v_mfma_f32_32x32x16_bf16 v[34:49], v[70:73], v[98:101], v[34:49]
	ds_read_b128 v[70:73], v131 offset:49152
	ds_read_b128 v[66:69], v130 offset:57344
	ds_read_b128 v[74:77], v131 offset:53248
	v_cndmask_b32_e64 v144, 31, v193, s[38:39]
	s_or_b64 vcc, s[22:23], vcc
	v_readfirstlane_b32 s6, v122
	s_waitcnt lgkmcnt(2)
	v_mfma_f32_32x32x16_bf16 v[50:65], v[70:73], v[86:89], v[50:65]
	ds_read_b128 v[70:73], v131 offset:57344
	s_waitcnt lgkmcnt(1)
	v_mfma_f32_32x32x16_bf16 v[34:49], v[74:77], v[86:89], v[34:49]
	ds_read_b128 v[74:77], v142 offset:49152
	ds_read_b128 v[78:81], v142 offset:53248
	s_waitcnt lgkmcnt(1)
	v_mfma_f32_32x32x16_bf16 v[50:65], v[74:77], v[82:85], v[50:65]
	s_waitcnt lgkmcnt(0)
	v_mfma_f32_32x32x16_bf16 v[34:49], v[78:81], v[82:85], v[34:49]
	ds_read_b128 v[78:81], v143 offset:49152
	ds_read_b128 v[74:77], v142 offset:57344
	ds_read_b128 v[112:115], v143 offset:53248
	s_waitcnt lgkmcnt(2)
	v_mfma_f32_32x32x16_bf16 v[50:65], v[78:81], v[90:93], v[50:65]
	ds_read_b128 v[78:81], v143 offset:57344
	s_waitcnt lgkmcnt(1)
	v_mfma_f32_32x32x16_bf16 v[34:49], v[112:115], v[90:93], v[34:49]
	s_nop 11
	v_cndmask_b32_e32 v123, v34, v225, vcc
	v_cmp_le_u32_e32 vcc, v162, v144
	s_nop 1
	v_cndmask_b32_e32 v113, v225, v50, vcc
	v_cmp_gt_u32_e32 vcc, v144, v162
	s_nop 1
	v_cndmask_b32_e32 v112, v225, v51, vcc
	v_cmp_ge_u32_e32 vcc, v125, v175
	s_nop 1
	v_cndmask_b32_e32 v117, v225, v36, vcc
	v_cmp_lt_u32_e32 vcc, v162, v125
	s_nop 1
	v_cndmask_b32_e32 v116, v225, v35, vcc
	v_cmp_le_u32_e32 vcc, v174, v144
	s_nop 1
	v_cndmask_b32_e32 v119, v225, v53, vcc
	v_cmp_le_u32_e32 vcc, v175, v144
	s_nop 1
	v_cndmask_b32_e32 v118, v225, v52, vcc
	v_cmp_le_u32_e32 vcc, v171, v125
	s_nop 1
	v_cndmask_b32_e32 v51, v225, v38, vcc
	v_cmp_le_u32_e32 vcc, v174, v125
	s_nop 1
	v_cndmask_b32_e32 v50, v225, v37, vcc
	v_cmp_le_u32_e32 vcc, v172, v144
	s_nop 1
	v_cndmask_b32_e32 v53, v225, v55, vcc
	v_cmp_le_u32_e32 vcc, v171, v144
	s_nop 1
	v_cndmask_b32_e32 v52, v225, v54, vcc
	v_cmp_le_u32_e32 vcc, v169, v125
	s_nop 1
	v_cndmask_b32_e32 v55, v225, v40, vcc
	v_cmp_le_u32_e32 vcc, v172, v125
	s_nop 1
	v_cndmask_b32_e32 v54, v225, v39, vcc
	v_cmp_le_u32_e32 vcc, v170, v144
	s_nop 1
	v_cndmask_b32_e32 v57, v225, v57, vcc
	v_cmp_le_u32_e32 vcc, v169, v144
	s_nop 1
	v_cndmask_b32_e32 v56, v225, v56, vcc
	v_cmp_le_u32_e32 vcc, v167, v125
	s_nop 1
	v_cndmask_b32_e32 v115, v225, v42, vcc
	v_cmp_le_u32_e32 vcc, v170, v125
	s_nop 1
	v_cndmask_b32_e32 v114, v225, v41, vcc
	v_cmp_le_u32_e32 vcc, v168, v144
	s_nop 1
	v_cndmask_b32_e32 v59, v225, v59, vcc
	v_cmp_le_u32_e32 vcc, v167, v144
	s_nop 1
	v_cndmask_b32_e32 v58, v225, v58, vcc
	v_cmp_le_u32_e32 vcc, v165, v125
	s_nop 1
	v_cndmask_b32_e32 v121, v225, v44, vcc
	v_cmp_le_u32_e32 vcc, v168, v125
	s_nop 1
	v_cndmask_b32_e32 v120, v225, v43, vcc
	v_cmp_le_u32_e32 vcc, v166, v144
	s_nop 1
	v_cndmask_b32_e32 v43, v225, v61, vcc
	v_cmp_le_u32_e32 vcc, v165, v144
	s_nop 1
	v_cndmask_b32_e32 v42, v225, v60, vcc
	v_cmp_le_u32_e32 vcc, v163, v125
	s_nop 1
	v_cndmask_b32_e32 v37, v225, v46, vcc
	v_cmp_le_u32_e32 vcc, v166, v125
	v_med3_f32 v46, v118, v119, s30
	s_nop 0
	v_cndmask_b32_e32 v36, v225, v45, vcc
	v_cmp_le_u32_e32 vcc, v164, v144
	v_med3_f32 v45, v113, v112, s30
	v_med3_f32 v45, v45, v46, s30
	v_cndmask_b32_e32 v39, v225, v63, vcc
	v_cmp_le_u32_e32 vcc, v163, v144
	v_med3_f32 v46, v52, v53, s30
	s_nop 0
	v_cndmask_b32_e32 v38, v225, v62, vcc
	v_cmp_le_u32_e32 vcc, v97, v125
	s_nop 1
	v_cndmask_b32_e32 v35, v225, v48, vcc
	v_cmp_le_u32_e32 vcc, v164, v125
	s_nop 1
	v_cndmask_b32_e32 v34, v225, v47, vcc
	v_cmp_le_u32_e32 vcc, v173, v144
	v_med3_f32 v47, v56, v57, s30
	v_med3_f32 v46, v46, v47, s30
	v_cndmask_b32_e32 v41, v225, v65, vcc
	v_cmp_le_u32_e32 vcc, v97, v144
	v_med3_f32 v45, v45, v46, s30
	v_med3_f32 v46, v58, v59, s30
	v_cndmask_b32_e32 v40, v225, v64, vcc
	v_med3_f32 v47, v42, v43, s30
	v_med3_f32 v46, v46, v47, s30
	v_med3_f32 v47, v38, v39, s30
	v_med3_f32 v48, v40, v41, s30
	v_med3_f32 v47, v47, v48, s30
	v_med3_f32 v46, v46, v47, s30
	v_med3_f32 v45, v45, v46, s30
	v_med3_f32 v46, v123, v116, s30
	v_med3_f32 v47, v117, v50, s30
	v_med3_f32 v46, v46, v47, s30
	v_med3_f32 v47, v51, v54, s30
	v_med3_f32 v48, v55, v114, s30
	v_cmp_le_u32_e32 vcc, v173, v125
	v_med3_f32 v47, v47, v48, s30
	v_med3_f32 v46, v46, v47, s30
	v_cndmask_b32_e32 v44, v225, v49, vcc
	v_med3_f32 v47, v115, v120, s30
	v_med3_f32 v48, v121, v36, s30
	v_med3_f32 v47, v47, v48, s30
	v_med3_f32 v48, v37, v34, s30
	v_med3_f32 v49, v35, v44, s30
	v_med3_f32 v48, v48, v49, s30
	v_med3_f32 v47, v47, v48, s30
	v_med3_f32 v46, v46, v47, s30
	v_med3_f32 v45, v45, v46, s30
	v_mov_b32_e32 v46, v45
	s_nop 1
	v_permlane32_swap_b32_e32 v45, v46
	v_max_f32_e32 v45, v45, v46
	v_cmp_gt_f32_e32 vcc, v45, v124
	s_cbranch_vccz .LBB0_124
	s_nop 0
	v_cndmask_b32_e32 v46, 0, v45, vcc
	v_exp_f32_e64 v48, -v46
	v_sub_f32_e32 v123, v123, v46
	v_pk_add_f32 v[112:113], v[112:113], v[46:47] op_sel_hi:[1,0] neg_lo:[0,1] neg_hi:[0,1]
	v_pk_add_f32 v[116:117], v[116:117], v[46:47] op_sel_hi:[1,0] neg_lo:[0,1] neg_hi:[0,1]
	v_mul_f32_e32 v127, v127, v48
	v_pk_add_f32 v[118:119], v[118:119], v[46:47] op_sel_hi:[1,0] neg_lo:[0,1] neg_hi:[0,1]
	v_pk_add_f32 v[50:51], v[50:51], v[46:47] op_sel_hi:[1,0] neg_lo:[0,1] neg_hi:[0,1]
	v_pk_add_f32 v[52:53], v[52:53], v[46:47] op_sel_hi:[1,0] neg_lo:[0,1] neg_hi:[0,1]
	v_pk_add_f32 v[54:55], v[54:55], v[46:47] op_sel_hi:[1,0] neg_lo:[0,1] neg_hi:[0,1]
	v_pk_add_f32 v[56:57], v[56:57], v[46:47] op_sel_hi:[1,0] neg_lo:[0,1] neg_hi:[0,1]
	v_pk_add_f32 v[114:115], v[114:115], v[46:47] op_sel_hi:[1,0] neg_lo:[0,1] neg_hi:[0,1]
	v_pk_add_f32 v[58:59], v[58:59], v[46:47] op_sel_hi:[1,0] neg_lo:[0,1] neg_hi:[0,1]
	v_pk_add_f32 v[120:121], v[120:121], v[46:47] op_sel_hi:[1,0] neg_lo:[0,1] neg_hi:[0,1]
	v_pk_add_f32 v[42:43], v[42:43], v[46:47] op_sel_hi:[1,0] neg_lo:[0,1] neg_hi:[0,1]
	v_pk_add_f32 v[36:37], v[36:37], v[46:47] op_sel_hi:[1,0] neg_lo:[0,1] neg_hi:[0,1]
	v_pk_add_f32 v[38:39], v[38:39], v[46:47] op_sel_hi:[1,0] neg_lo:[0,1] neg_hi:[0,1]
	v_pk_add_f32 v[34:35], v[34:35], v[46:47] op_sel_hi:[1,0] neg_lo:[0,1] neg_hi:[0,1]
	v_pk_mul_f32 v[16:17], v[16:17], v[48:49] op_sel_hi:[1,0]
	v_pk_mul_f32 v[14:15], v[14:15], v[48:49] op_sel_hi:[1,0]
	v_pk_mul_f32 v[12:13], v[12:13], v[48:49] op_sel_hi:[1,0]
	v_pk_mul_f32 v[10:11], v[10:11], v[48:49] op_sel_hi:[1,0]
	v_pk_mul_f32 v[8:9], v[8:9], v[48:49] op_sel_hi:[1,0]
	v_pk_mul_f32 v[6:7], v[6:7], v[48:49] op_sel_hi:[1,0]
	v_pk_mul_f32 v[4:5], v[4:5], v[48:49] op_sel_hi:[1,0]
	v_pk_mul_f32 v[2:3], v[2:3], v[48:49] op_sel_hi:[1,0]
	v_pk_mul_f32 v[32:33], v[32:33], v[48:49] op_sel_hi:[1,0]
	v_pk_mul_f32 v[30:31], v[30:31], v[48:49] op_sel_hi:[1,0]
	v_pk_mul_f32 v[28:29], v[28:29], v[48:49] op_sel_hi:[1,0]
	v_pk_mul_f32 v[26:27], v[26:27], v[48:49] op_sel_hi:[1,0]
	v_pk_mul_f32 v[24:25], v[24:25], v[48:49] op_sel_hi:[1,0]
	v_pk_mul_f32 v[22:23], v[22:23], v[48:49] op_sel_hi:[1,0]
	v_pk_mul_f32 v[20:21], v[20:21], v[48:49] op_sel_hi:[1,0]
	v_pk_mul_f32 v[18:19], v[18:19], v[48:49] op_sel_hi:[1,0]
	v_pk_add_f32 v[40:41], v[40:41], v[46:47] op_sel_hi:[1,0] neg_lo:[0,1] neg_hi:[0,1]
	v_sub_f32_e32 v44, v44, v46
.LBB0_124:
	v_exp_f32_e32 v61, v113
	v_exp_f32_e32 v60, v123
	v_exp_f32_e32 v63, v112
	v_exp_f32_e32 v62, v116
	v_exp_f32_e32 v128, v114
	v_exp_f32_e32 v148, v115
	v_exp_f32_e32 v115, v42
	v_exp_f32_e32 v114, v121
	v_exp_f32_e32 v121, v43
	v_exp_f32_e32 v152, v44
	ds_read_b128 v[42:45], v130 offset:61440
	v_exp_f32_e32 v65, v118
	v_exp_f32_e32 v64, v117
	v_exp_f32_e32 v113, v119
	v_exp_f32_e32 v112, v50
	v_exp_f32_e32 v117, v52
	v_exp_f32_e32 v116, v51
	v_exp_f32_e32 v119, v53
	v_exp_f32_e32 v118, v54
	v_exp_f32_e32 v125, v56
	v_exp_f32_e32 v124, v55
	v_exp_f32_e32 v129, v57
	v_cvt_pk_bf16_f32 v46, v61, v63
	v_pk_add_f32 v[54:55], v[62:63], v[60:61]
	v_cvt_pk_bf16_f32 v47, v65, v113
	v_pk_add_f32 v[54:55], v[64:65], v[54:55]
	v_cvt_pk_bf16_f32 v48, v117, v119
	v_pk_add_f32 v[54:55], v[112:113], v[54:55]
	v_cvt_pk_bf16_f32 v49, v125, v129
	v_pk_add_f32 v[54:55], v[116:117], v[54:55]
	v_cvt_pk_bf16_f32 v50, v60, v62
	v_mfma_f32_32x32x16_bf16 v[2:17], v[66:69], v[46:49], v[2:17]
	v_add_f32_e64 v60, v118, v54
	v_add_f32_e64 v61, v119, v55
	ds_read_b128 v[54:57], v131 offset:61440
	v_exp_f32_e32 v149, v58
	v_exp_f32_e32 v59, v59
	v_exp_f32_e32 v58, v120
	v_exp_f32_e32 v151, v38
	v_exp_f32_e32 v67, v39
	s_waitcnt lgkmcnt(1)
	v_mfma_f32_32x32x16_bf16 v[18:33], v[42:45], v[46:49], v[18:33]
	v_exp_f32_e32 v69, v40
	v_exp_f32_e32 v153, v41
	v_pk_add_f32 v[42:43], v[124:125], v[60:61]
	v_exp_f32_e32 v120, v36
	v_pk_add_f32 v[42:43], v[128:129], v[42:43]
	v_cvt_pk_bf16_f32 v38, v149, v59
	v_pk_add_f32 v[42:43], v[148:149], v[42:43]
	v_cvt_pk_bf16_f32 v39, v115, v121
	v_pk_add_f32 v[42:43], v[58:59], v[42:43]
	v_cvt_pk_bf16_f32 v40, v151, v67
	v_cvt_pk_bf16_f32 v41, v69, v153
	v_exp_f32_e32 v150, v37
	v_pk_add_f32 v[42:43], v[114:115], v[42:43]
	v_mfma_f32_32x32x16_bf16 v[2:17], v[70:73], v[38:41], v[2:17]
	v_exp_f32_e32 v66, v34
	v_pk_add_f32 v[46:47], v[120:121], v[42:43]
	ds_read_b128 v[42:45], v142 offset:61440
	v_exp_f32_e32 v68, v35
	v_cvt_pk_bf16_f32 v51, v64, v112
	v_cvt_pk_bf16_f32 v52, v116, v118
	v_cvt_pk_bf16_f32 v53, v124, v128
	s_waitcnt lgkmcnt(1)
	v_mfma_f32_32x32x16_bf16 v[18:33], v[54:57], v[38:41], v[18:33]
	v_add_f32_e64 v38, v150, v46
	v_add_f32_e64 v39, v151, v47
	v_cvt_pk_bf16_f32 v34, v148, v58
	v_add_f32_e64 v38, v66, v38
	v_add_f32_e64 v39, v67, v39
	v_cvt_pk_bf16_f32 v35, v114, v120
	v_pk_add_f32 v[38:39], v[68:69], v[38:39]
	v_cvt_pk_bf16_f32 v36, v150, v66
	v_pk_add_f32 v[38:39], v[152:153], v[38:39]
	v_mfma_f32_32x32x16_bf16 v[2:17], v[74:77], v[50:53], v[2:17]
	v_add_f32_e32 v38, v38, v39
	v_add_f32_e32 v46, v127, v38
	ds_read_b128 v[38:41], v143 offset:61440
	v_cvt_pk_bf16_f32 v37, v68, v152
	s_lshl_b32 s3, s6, 14
	s_and_b32 s3, s3, 0x4000
	s_add_i32 s40, s3, 0
	s_waitcnt lgkmcnt(1)
	v_mfma_f32_32x32x16_bf16 v[18:33], v[42:45], v[50:53], v[18:33]
	v_mov_b32_e32 v42, v46
	s_nop 1
	v_permlane32_swap_b32_e32 v46, v42
	v_add_f32_e32 v42, v46, v42
	v_rcp_f32_e32 v43, v42
	v_cmp_lt_f32_e32 vcc, 0, v42
	s_cmp_lt_i32 s6, s2
	v_mfma_f32_32x32x16_bf16 v[2:17], v[78:81], v[34:37], v[2:17]
	s_cselect_b64 s[22:23], -1, 0
	s_cmp_ge_i32 s6, s2
	s_waitcnt lgkmcnt(0)
	v_mfma_f32_32x32x16_bf16 v[18:33], v[38:41], v[34:37], v[18:33]
	v_mul_f32_e32 v34, v191, v43
	v_cndmask_b32_e32 v50, 0, v34, vcc
	ds_read2st64_b32 v[34:35], v132 offset1:1
	ds_read2st64_b32 v[36:37], v132 offset0:16 offset1:17
	ds_read2st64_b32 v[38:39], v132 offset0:2 offset1:3
	ds_read2st64_b32 v[40:41], v132 offset0:4 offset1:5
	ds_read2st64_b32 v[42:43], v132 offset0:6 offset1:7
	ds_read2st64_b32 v[44:45], v132 offset0:18 offset1:19
	ds_read2st64_b32 v[46:47], v132 offset0:20 offset1:21
	ds_read2st64_b32 v[48:49], v132 offset0:22 offset1:23
	s_waitcnt lgkmcnt(7)
	v_fma_f32 v2, v2, v50, v34
	v_fmac_f32_e32 v35, v3, v50
	ds_write2st64_b32 v132, v2, v35 offset1:1
	s_waitcnt lgkmcnt(6)
	v_fma_f32 v2, v4, v50, v38
	s_waitcnt lgkmcnt(3)
	v_fma_f32 v3, v20, v50, v44
	v_fmac_f32_e32 v39, v5, v50
	v_fmac_f32_e32 v45, v21, v50
	ds_write2st64_b32 v132, v2, v39 offset0:2 offset1:3
	ds_write2st64_b32 v132, v3, v45 offset0:18 offset1:19
	v_fma_f32 v2, v6, v50, v40
	s_waitcnt lgkmcnt(4)
	v_fma_f32 v3, v22, v50, v46
	v_fmac_f32_e32 v41, v7, v50
	v_fmac_f32_e32 v47, v23, v50
	v_fma_f32 v18, v18, v50, v36
	v_fmac_f32_e32 v37, v19, v50
	ds_write2st64_b32 v132, v2, v41 offset0:4 offset1:5
	ds_write2st64_b32 v132, v3, v47 offset0:20 offset1:21
	v_fma_f32 v2, v8, v50, v42
	s_waitcnt lgkmcnt(5)
	v_fma_f32 v3, v24, v50, v48
	v_fmac_f32_e32 v43, v9, v50
	v_fmac_f32_e32 v49, v25, v50
	ds_write2st64_b32 v132, v18, v37 offset0:16 offset1:17
	ds_write2st64_b32 v132, v2, v43 offset0:6 offset1:7
	ds_write2st64_b32 v132, v3, v49 offset0:22 offset1:23
	ds_read2st64_b32 v[2:3], v132 offset0:8 offset1:9
	ds_read2st64_b32 v[4:5], v132 offset0:24 offset1:25
	ds_read2st64_b32 v[6:7], v132 offset0:10 offset1:11
	ds_read2st64_b32 v[8:9], v132 offset0:12 offset1:13
	ds_read2st64_b32 v[18:19], v132 offset0:14 offset1:15
	ds_read2st64_b32 v[20:21], v132 offset0:26 offset1:27
	ds_read2st64_b32 v[22:23], v132 offset0:28 offset1:29
	ds_read2st64_b32 v[24:25], v132 offset0:30 offset1:31
	s_waitcnt lgkmcnt(7)
	v_fma_f32 v2, v10, v50, v2
	v_fmac_f32_e32 v3, v11, v50
	ds_write2st64_b32 v132, v2, v3 offset0:8 offset1:9
	s_waitcnt lgkmcnt(6)
	v_fma_f32 v2, v12, v50, v6
	v_fmac_f32_e32 v7, v13, v50
	s_waitcnt lgkmcnt(3)
	v_fma_f32 v3, v28, v50, v20
	ds_write2st64_b32 v132, v2, v7 offset0:10 offset1:11
	v_fmac_f32_e32 v21, v29, v50
	v_fma_f32 v2, v14, v50, v8
	v_fmac_f32_e32 v9, v15, v50
	ds_write2st64_b32 v132, v3, v21 offset0:26 offset1:27
	s_waitcnt lgkmcnt(4)
	v_fma_f32 v3, v30, v50, v22
	ds_write2st64_b32 v132, v2, v9 offset0:12 offset1:13
	v_fmac_f32_e32 v23, v31, v50
	v_fma_f32 v2, v16, v50, v18
	v_fmac_f32_e32 v19, v17, v50
	ds_write2st64_b32 v132, v3, v23 offset0:28 offset1:29
	s_waitcnt lgkmcnt(5)
	v_fma_f32 v3, v32, v50, v24
	ds_write2st64_b32 v132, v2, v19 offset0:14 offset1:15
	v_fmac_f32_e32 v25, v33, v50
	v_add_u32_e32 v2, s40, v133
	v_fma_f32 v4, v26, v50, v4
	v_fmac_f32_e32 v5, v27, v50
	ds_write2st64_b32 v132, v3, v25 offset0:30 offset1:31
	v_add_u32_e32 v3, v2, v134
	ds_write2st64_b32 v132, v4, v5 offset0:24 offset1:25
	s_waitcnt lgkmcnt(0)
	s_barrier
	s_waitcnt vmcnt(1)
	ds_write_b128 v3, v[106:109] offset:49152
	v_add3_u32 v3, v2, v135, v136
	v_add3_u32 v2, v2, v137, v136
	s_waitcnt vmcnt(0)
	ds_write_b64 v3, v[102:103] offset:57344
	ds_write_b64 v2, v[104:105] offset:57344
	s_cbranch_scc1 .LBB0_126
	v_lshlrev_b32_e32 v4, 6, v122
	v_lshlrev_b32_e32 v4, 7, v4
	v_add_u32_e32 v4, 0x2000, v4
	v_mov_b32_e32 v5, v1
	v_lshl_add_u64 v[4:5], s[0:1], 0, v[4:5]
	s_mov_b64 s[30:31], 0xa80000
	v_lshl_add_u64 v[4:5], v[194:195], 1, v[4:5]
	v_lshl_add_u64 v[2:3], v[110:111], 0, s[30:31]
	global_load_dwordx4 v[106:109], v[4:5], off
	global_load_dwordx4 v[102:105], v[2:3], off offset:128

.LBB0_129:
	s_nop 8
	v_max3_f32 v3, v34, v35, v36
	v_max3_f32 v3, v3, v37, v38
	v_max3_f32 v3, v3, v39, v40
	v_max3_f32 v3, v3, v41, v42
	v_max3_f32 v3, v3, v43, v44
	v_max3_f32 v3, v3, v45, v46
	v_max3_f32 v3, v3, v47, v48
	v_max3_f32 v4, v50, v51, v52
	v_max3_f32 v4, v4, v53, v54
	v_max3_f32 v4, v4, v55, v56
	v_max3_f32 v4, v4, v57, v58
	v_max3_f32 v4, v4, v59, v60
	v_max3_f32 v4, v4, v61, v62
	v_max3_f32 v4, v4, v63, v64
	v_max3_f32 v2, v3, v4, v49
	v_max_f32_e32 v2, v2, v65
	v_mov_b32_e32 v3, v2
	s_nop 1
	v_permlane32_swap_b32_e32 v2, v3
	v_max_f32_e32 v2, v2, v3
	v_cmp_lt_f32_e64 s[36:37], s24, v2
	s_mov_b64 vcc, s[36:37]
	s_cbranch_vccz .LBB0_139
	v_cndmask_b32_e64 v4, 0, v2, s[36:37]
	v_exp_f32_e64 v2, -v4
	v_add_f32_e32 v150, 0, v4
	v_xor_b32_e32 v18, 0x80000000, v150
	v_pk_add_f32 v[34:35], v[34:35], v[4:5] op_sel_hi:[1,0] neg_lo:[0,1] neg_hi:[0,1]
	v_mul_f32_e32 v2, 0, v2
	v_pk_add_f32 v[50:51], v[50:51], v[4:5] op_sel_hi:[1,0] neg_lo:[0,1] neg_hi:[0,1]
	v_pk_add_f32 v[36:37], v[36:37], v[4:5] op_sel_hi:[1,0] neg_lo:[0,1] neg_hi:[0,1]
	v_pk_add_f32 v[52:53], v[52:53], v[4:5] op_sel_hi:[1,0] neg_lo:[0,1] neg_hi:[0,1]
	v_pk_add_f32 v[38:39], v[38:39], v[4:5] op_sel_hi:[1,0] neg_lo:[0,1] neg_hi:[0,1]
	v_pk_add_f32 v[54:55], v[54:55], v[4:5] op_sel_hi:[1,0] neg_lo:[0,1] neg_hi:[0,1]
	v_pk_add_f32 v[40:41], v[40:41], v[4:5] op_sel_hi:[1,0] neg_lo:[0,1] neg_hi:[0,1]
	v_pk_add_f32 v[56:57], v[56:57], v[4:5] op_sel_hi:[1,0] neg_lo:[0,1] neg_hi:[0,1]
	v_pk_add_f32 v[42:43], v[42:43], v[4:5] op_sel_hi:[1,0] neg_lo:[0,1] neg_hi:[0,1]
	v_pk_add_f32 v[58:59], v[58:59], v[4:5] op_sel_hi:[1,0] neg_lo:[0,1] neg_hi:[0,1]
	v_pk_add_f32 v[44:45], v[44:45], v[4:5] op_sel_hi:[1,0] neg_lo:[0,1] neg_hi:[0,1]
	v_pk_add_f32 v[60:61], v[60:61], v[4:5] op_sel_hi:[1,0] neg_lo:[0,1] neg_hi:[0,1]
	v_pk_add_f32 v[46:47], v[46:47], v[4:5] op_sel_hi:[1,0] neg_lo:[0,1] neg_hi:[0,1]
	v_pk_add_f32 v[62:63], v[62:63], v[4:5] op_sel_hi:[1,0] neg_lo:[0,1] neg_hi:[0,1]
	v_pk_add_f32 v[48:49], v[48:49], v[4:5] op_sel_hi:[1,0] neg_lo:[0,1] neg_hi:[0,1]
	v_pk_add_f32 v[64:65], v[64:65], v[4:5] op_sel_hi:[1,0] neg_lo:[0,1] neg_hi:[0,1]
	v_mov_b32_e32 v19, v18
	v_mov_b32_e32 v20, v18
	v_mov_b32_e32 v21, v18
	v_mov_b32_e32 v22, v18
	v_mov_b32_e32 v23, v18
	v_mov_b32_e32 v24, v18
	v_mov_b32_e32 v25, v18
	v_mov_b32_e32 v26, v18
	v_mov_b32_e32 v27, v18
	v_mov_b32_e32 v28, v18
	v_mov_b32_e32 v29, v18
	v_mov_b32_e32 v30, v18
	v_mov_b32_e32 v31, v18
	v_mov_b32_e32 v32, v18
	v_mov_b32_e32 v33, v18
	s_branch .LBB0_140

.LBB0_137:
	s_nop 4
	v_max3_f32 v82, v50, v51, v52
	v_max3_f32 v82, v82, v53, v54
	v_max3_f32 v82, v82, v55, v56
	v_max3_f32 v82, v82, v57, v58
	v_max3_f32 v82, v82, v59, v60
	v_max3_f32 v82, v82, v61, v62
	v_max3_f32 v82, v82, v63, v64
	v_max3_f32 v83, v18, v19, v20
	v_max3_f32 v83, v83, v21, v22
	v_max3_f32 v83, v83, v23, v24
	v_max3_f32 v83, v83, v25, v26
	v_max3_f32 v83, v83, v27, v28
	v_max3_f32 v83, v83, v29, v30
	v_max3_f32 v83, v83, v31, v32
	v_max3_f32 v0, v82, v83, v65
	v_max_f32_e32 v0, v0, v33
	v_mov_b32_e32 v82, v0
	s_nop 1
	v_permlane32_swap_b32_e32 v0, v82
	v_max_f32_e32 v0, v0, v82
	v_cndmask_b32_e64 v82, v227, v228, s[18:19]
	v_cmp_gt_f32_e32 vcc, v0, v82
	s_cbranch_vccz .LBB0_60
	s_nop 0
	v_cndmask_b32_e32 v0, 0, v0, vcc
	v_exp_f32_e64 v82, -v0
	v_pk_add_f32 v[50:51], v[50:51], v[0:1] op_sel_hi:[1,0] neg_lo:[0,1] neg_hi:[0,1]
	v_pk_add_f32 v[18:19], v[18:19], v[0:1] op_sel_hi:[1,0] neg_lo:[0,1] neg_hi:[0,1]
	v_pk_add_f32 v[52:53], v[52:53], v[0:1] op_sel_hi:[1,0] neg_lo:[0,1] neg_hi:[0,1]
	v_mul_f32_e32 v149, v149, v82
	v_pk_add_f32 v[20:21], v[20:21], v[0:1] op_sel_hi:[1,0] neg_lo:[0,1] neg_hi:[0,1]
	v_pk_add_f32 v[54:55], v[54:55], v[0:1] op_sel_hi:[1,0] neg_lo:[0,1] neg_hi:[0,1]
	v_pk_add_f32 v[22:23], v[22:23], v[0:1] op_sel_hi:[1,0] neg_lo:[0,1] neg_hi:[0,1]
	v_pk_add_f32 v[56:57], v[56:57], v[0:1] op_sel_hi:[1,0] neg_lo:[0,1] neg_hi:[0,1]
	v_pk_add_f32 v[24:25], v[24:25], v[0:1] op_sel_hi:[1,0] neg_lo:[0,1] neg_hi:[0,1]
	v_pk_add_f32 v[58:59], v[58:59], v[0:1] op_sel_hi:[1,0] neg_lo:[0,1] neg_hi:[0,1]
	v_pk_add_f32 v[26:27], v[26:27], v[0:1] op_sel_hi:[1,0] neg_lo:[0,1] neg_hi:[0,1]
	v_pk_add_f32 v[60:61], v[60:61], v[0:1] op_sel_hi:[1,0] neg_lo:[0,1] neg_hi:[0,1]
	v_pk_add_f32 v[28:29], v[28:29], v[0:1] op_sel_hi:[1,0] neg_lo:[0,1] neg_hi:[0,1]
	v_pk_add_f32 v[62:63], v[62:63], v[0:1] op_sel_hi:[1,0] neg_lo:[0,1] neg_hi:[0,1]
	v_pk_add_f32 v[30:31], v[30:31], v[0:1] op_sel_hi:[1,0] neg_lo:[0,1] neg_hi:[0,1]
	v_pk_mul_f32 v[48:49], v[48:49], v[82:83] op_sel_hi:[1,0]
	v_pk_mul_f32 v[46:47], v[46:47], v[82:83] op_sel_hi:[1,0]
	v_pk_mul_f32 v[44:45], v[44:45], v[82:83] op_sel_hi:[1,0]
	v_pk_mul_f32 v[42:43], v[42:43], v[82:83] op_sel_hi:[1,0]
	v_pk_mul_f32 v[40:41], v[40:41], v[82:83] op_sel_hi:[1,0]
	v_pk_mul_f32 v[38:39], v[38:39], v[82:83] op_sel_hi:[1,0]
	v_pk_mul_f32 v[36:37], v[36:37], v[82:83] op_sel_hi:[1,0]
	v_pk_mul_f32 v[34:35], v[34:35], v[82:83] op_sel_hi:[1,0]
	v_pk_mul_f32 v[16:17], v[16:17], v[82:83] op_sel_hi:[1,0]
	v_pk_mul_f32 v[14:15], v[14:15], v[82:83] op_sel_hi:[1,0]
	v_pk_mul_f32 v[12:13], v[12:13], v[82:83] op_sel_hi:[1,0]
	v_pk_mul_f32 v[10:11], v[10:11], v[82:83] op_sel_hi:[1,0]
	v_pk_mul_f32 v[8:9], v[8:9], v[82:83] op_sel_hi:[1,0]
	v_pk_mul_f32 v[6:7], v[6:7], v[82:83] op_sel_hi:[1,0]
	v_pk_mul_f32 v[4:5], v[4:5], v[82:83] op_sel_hi:[1,0]
	v_pk_mul_f32 v[2:3], v[2:3], v[82:83] op_sel_hi:[1,0]
	v_pk_add_f32 v[64:65], v[64:65], v[0:1] op_sel_hi:[1,0] neg_lo:[0,1] neg_hi:[0,1]
	v_pk_add_f32 v[32:33], v[32:33], v[0:1] op_sel_hi:[1,0] neg_lo:[0,1] neg_hi:[0,1]
	s_branch .LBB0_60

.LBB0_140:
	v_exp_f32_e32 v115, v34
	v_exp_f32_e32 v114, v50
	v_exp_f32_e32 v35, v35
	v_exp_f32_e32 v34, v51
	v_exp_f32_e32 v117, v36
	v_exp_f32_e32 v116, v52
	v_exp_f32_e32 v37, v37
	v_exp_f32_e32 v36, v53
	v_exp_f32_e32 v119, v38
	v_exp_f32_e32 v118, v54
	v_pk_add_f32 v[50:51], v[34:35], v[114:115]
	v_exp_f32_e32 v39, v39
	v_exp_f32_e32 v38, v55
	v_pk_add_f32 v[50:51], v[116:117], v[50:51]
	v_exp_f32_e32 v121, v40
	v_exp_f32_e32 v120, v56
	v_pk_add_f32 v[50:51], v[36:37], v[50:51]
	v_exp_f32_e32 v41, v41
	v_exp_f32_e32 v40, v57
	v_exp_f32_e32 v123, v42
	v_exp_f32_e32 v122, v58
	v_pk_add_f32 v[50:51], v[118:119], v[50:51]
	v_exp_f32_e32 v43, v43
	v_exp_f32_e32 v42, v59
	v_pk_add_f32 v[50:51], v[38:39], v[50:51]
	v_exp_f32_e32 v125, v44
	v_exp_f32_e32 v124, v60
	v_pk_add_f32 v[50:51], v[120:121], v[50:51]
	v_exp_f32_e32 v45, v45
	v_exp_f32_e32 v44, v61
	v_pk_add_f32 v[50:51], v[40:41], v[50:51]
	v_exp_f32_e32 v129, v46
	v_exp_f32_e32 v128, v62
	v_pk_add_f32 v[50:51], v[122:123], v[50:51]
	v_exp_f32_e32 v47, v47
	v_exp_f32_e32 v46, v63
	v_pk_add_f32 v[50:51], v[42:43], v[50:51]
	v_exp_f32_e32 v153, v48
	v_exp_f32_e32 v152, v64
	v_pk_add_f32 v[50:51], v[124:125], v[50:51]
	v_exp_f32_e32 v49, v49
	v_exp_f32_e32 v48, v65
	v_pk_add_f32 v[50:51], v[44:45], v[50:51]
	v_cvt_pk_bf16_f32 v52, v119, v39
	v_pk_add_f32 v[50:51], v[128:129], v[50:51]
	v_cvt_pk_bf16_f32 v53, v121, v41
	v_pk_add_f32 v[50:51], v[46:47], v[50:51]
	v_cvt_pk_bf16_f32 v54, v123, v43
	v_pk_add_f32 v[50:51], v[152:153], v[50:51]
	v_cvt_pk_bf16_f32 v55, v125, v45
	v_pk_add_f32 v[50:51], v[48:49], v[50:51]
	v_cvt_pk_bf16_f32 v58, v114, v34
	v_add_f32_e32 v127, v50, v51
	v_cvt_pk_bf16_f32 v50, v115, v35
	v_cvt_pk_bf16_f32 v51, v117, v37
	v_cvt_pk_bf16_f32 v59, v116, v36
	v_cvt_pk_bf16_f32 v60, v118, v38
	v_cvt_pk_bf16_f32 v61, v120, v40
	v_cvt_pk_bf16_f32 v62, v122, v42
	v_cvt_pk_bf16_f32 v63, v124, v44
	ds_read_b128 v[114:117], v110 offset:61440
	ds_read_b128 v[118:121], v111 offset:61440
	ds_read_b128 v[122:125], v112 offset:61440
	ds_read_b128 v[110:113], v113 offset:61440
	v_mov_b32_e32 v3, v2
	v_mov_b32_e32 v4, v2
	v_mov_b32_e32 v5, v2
	v_mov_b32_e32 v6, v2
	v_mov_b32_e32 v7, v2
	v_mov_b32_e32 v8, v2
	v_mov_b32_e32 v9, v2
	v_mov_b32_e32 v10, v2
	v_mov_b32_e32 v11, v2
	v_mov_b32_e32 v12, v2
	v_mov_b32_e32 v13, v2
	v_mov_b32_e32 v14, v2
	v_mov_b32_e32 v15, v2
	v_mov_b32_e32 v16, v2
	v_mov_b32_e32 v17, v2
	v_cvt_pk_bf16_f32 v56, v129, v47
	v_cvt_pk_bf16_f32 v57, v153, v49
	v_cvt_pk_bf16_f32 v64, v128, v46
	v_cvt_pk_bf16_f32 v65, v152, v48
	v_add_f32_e32 v149, v2, v127
	v_mfma_f32_32x32x16_bf16 v[34:49], v[78:81], v[50:53], v[2:17]
	s_waitcnt lgkmcnt(3)
	v_mfma_f32_32x32x16_bf16 v[2:17], v[114:117], v[50:53], v[2:17]
	v_mfma_f32_32x32x16_bf16 v[34:49], v[74:77], v[54:57], v[34:49]
	s_waitcnt lgkmcnt(2)
	v_mfma_f32_32x32x16_bf16 v[2:17], v[118:121], v[54:57], v[2:17]
	v_mfma_f32_32x32x16_bf16 v[34:49], v[70:73], v[58:61], v[34:49]
	s_waitcnt lgkmcnt(1)
	v_mfma_f32_32x32x16_bf16 v[2:17], v[122:125], v[58:61], v[2:17]
	v_mfma_f32_32x32x16_bf16 v[34:49], v[66:69], v[62:65], v[34:49]
	s_waitcnt lgkmcnt(0)
	v_mfma_f32_32x32x16_bf16 v[2:17], v[110:113], v[62:65], v[2:17]
	s_max_u32 s1, s2, 8
	s_add_i32 s0, s1, -7
	s_cmp_ge_i32 s0, s2
	s_cbranch_scc1 .LBB0_132

.LBB0_142:
	v_exp_f32_e32 v157, v66
	v_exp_f32_e32 v159, v67
	v_exp_f32_e32 v161, v68
	v_exp_f32_e32 v177, v69
	ds_read_b128 v[66:69], v154 offset:61440
	v_exp_f32_e32 v179, v70
	v_exp_f32_e32 v181, v71
	v_exp_f32_e32 v183, v72
	v_exp_f32_e32 v185, v73
	v_exp_f32_e32 v156, v50
	v_exp_f32_e32 v158, v51
	v_exp_f32_e32 v160, v52
	v_exp_f32_e32 v176, v53
	v_cvt_pk_bf16_f32 v50, v157, v159
	v_cvt_pk_bf16_f32 v51, v161, v177
	v_cvt_pk_bf16_f32 v52, v179, v181
	v_cvt_pk_bf16_f32 v53, v183, v185
	ds_read_b128 v[70:73], v153 offset:61440
	v_exp_f32_e32 v178, v54
	s_waitcnt lgkmcnt(5)
	v_mfma_f32_32x32x16_bf16 v[34:49], v[114:117], v[50:53], v[34:49]
	v_exp_f32_e32 v187, v74
	v_exp_f32_e32 v75, v75
	v_exp_f32_e32 v189, v76
	v_exp_f32_e32 v77, v77
	v_exp_f32_e32 v191, v78
	v_exp_f32_e32 v79, v79
	v_exp_f32_e32 v115, v80
	s_waitcnt lgkmcnt(1)
	v_mfma_f32_32x32x16_bf16 v[2:17], v[66:69], v[50:53], v[2:17]
	v_exp_f32_e32 v81, v81
	v_exp_f32_e32 v180, v55
	v_pk_add_f32 v[50:51], v[158:159], v[156:157]
	v_exp_f32_e32 v182, v56
	v_pk_add_f32 v[50:51], v[160:161], v[50:51]
	v_exp_f32_e32 v184, v57
	v_pk_add_f32 v[50:51], v[176:177], v[50:51]
	v_cvt_pk_bf16_f32 v54, v187, v75
	v_cvt_pk_bf16_f32 v55, v189, v77
	v_cvt_pk_bf16_f32 v56, v191, v79
	v_cvt_pk_bf16_f32 v57, v115, v81
	v_pk_add_f32 v[66:67], v[178:179], v[50:51]
	ds_read_b128 v[50:53], v152 offset:61440
	v_mfma_f32_32x32x16_bf16 v[34:49], v[110:113], v[54:57], v[34:49]
	v_exp_f32_e32 v186, v58
	v_exp_f32_e32 v74, v59
	v_exp_f32_e32 v188, v60
	v_exp_f32_e32 v76, v61
	v_cvt_pk_bf16_f32 v58, v156, v158
	v_cvt_pk_bf16_f32 v59, v160, v176
	v_cvt_pk_bf16_f32 v60, v178, v180
	s_waitcnt lgkmcnt(1)
	v_mfma_f32_32x32x16_bf16 v[2:17], v[70:73], v[54:57], v[2:17]
	v_add_f32_e64 v54, v180, v66
	v_add_f32_e64 v55, v181, v67
	v_cvt_pk_bf16_f32 v61, v182, v184
	v_add_f32_e64 v54, v182, v54
	v_add_f32_e64 v55, v183, v55
	v_exp_f32_e32 v190, v62
	v_pk_add_f32 v[54:55], v[184:185], v[54:55]
	v_exp_f32_e32 v78, v63
	v_pk_add_f32 v[54:55], v[186:187], v[54:55]
	v_mfma_f32_32x32x16_bf16 v[34:49], v[118:121], v[58:61], v[34:49]
	v_add_f32_e64 v54, v74, v54
	v_add_f32_e64 v55, v75, v55
	v_exp_f32_e32 v114, v64
	v_pk_add_f32 v[66:67], v[188:189], v[54:55]
	ds_read_b128 v[54:57], v151 offset:61440
	v_exp_f32_e32 v80, v65
	v_cvt_pk_bf16_f32 v62, v186, v74
	v_cvt_pk_bf16_f32 v63, v188, v76
	s_waitcnt lgkmcnt(1)
	v_mfma_f32_32x32x16_bf16 v[2:17], v[50:53], v[58:61], v[2:17]
	v_cvt_pk_bf16_f32 v64, v190, v78
	v_cvt_pk_bf16_f32 v65, v114, v80
	v_add_f32_e64 v50, v76, v66
	v_add_f32_e64 v51, v77, v67
	v_cmp_lt_f32_e32 vcc, s24, v155
	v_pk_add_f32 v[50:51], v[190:191], v[50:51]
	s_or_b64 s[18:19], s[36:37], vcc
	v_pk_add_f32 v[50:51], v[78:79], v[50:51]
	v_mfma_f32_32x32x16_bf16 v[34:49], v[122:125], v[62:65], v[34:49]
	v_add_f32_e64 v50, v114, v50
	v_add_f32_e64 v51, v115, v51
	s_andn2_b64 s[30:31], s[36:37], exec
	v_add_f32_e64 v50, v80, v50
	v_add_f32_e64 v51, v81, v51
	s_and_b64 s[36:37], s[18:19], exec
	s_add_i32 s0, s0, 1
	v_add_f32_e32 v50, v50, v51
	s_addk_i32 s1, 0x4000
	s_waitcnt lgkmcnt(0)
	v_mfma_f32_32x32x16_bf16 v[2:17], v[54:57], v[62:65], v[2:17]
	s_or_b64 s[36:37], s[30:31], s[36:37]
	v_add_f32_e32 v149, v149, v50
	v_lshl_add_u64 v[126:127], v[126:127], 0, s[34:35]
	s_cmp_ge_u32 s0, s2
	v_lshl_add_u64 v[128:129], v[128:129], 0, s[26:27]
	s_cbranch_scc1 .LBB0_133
.LBB0_143:
	s_and_b32 s6, s1, 0x4000
	s_add_i32 s18, s6, 0
	v_add_u32_e32 v50, s18, v133
	v_add_u32_e32 v51, v50, v134
	s_waitcnt vmcnt(1)
	ds_write_b128 v51, v[106:109] offset:49152
	v_add3_u32 v51, v50, v135, v136
	v_add3_u32 v50, v50, v137, v136
	s_waitcnt vmcnt(0)
	ds_write_b64 v51, v[102:103] offset:57344
	ds_write_b64 v50, v[104:105] offset:57344
	global_load_dwordx4 v[106:109], v[128:129], off
	global_load_dwordx4 v[102:105], v[126:127], off
	v_add_u32_e32 v54, s18, v0
	s_mov_b32 s6, 0x7f800000
	v_add_u32_e32 v154, v54, v138
	s_waitcnt lgkmcnt(0)
	s_barrier
	ds_read_b128 v[50:53], v154 offset:49152
	v_add_u32_e32 v153, v54, v139
	ds_read_b128 v[110:113], v153 offset:49152
	s_waitcnt lgkmcnt(1)
	v_mfma_f32_32x32x16_bf16 v[66:81], v[50:53], v[98:101], v[18:33]
	v_add_u32_e32 v152, v54, v140
	v_add_u32_e32 v151, v54, v141
	ds_read_b128 v[114:117], v152 offset:49152
	ds_read_b128 v[118:121], v151 offset:49152
	ds_read_b128 v[122:125], v154 offset:53248
	ds_read_b128 v[156:159], v153 offset:53248
	ds_read_b128 v[176:179], v152 offset:53248
	ds_read_b128 v[180:183], v151 offset:53248
	s_waitcnt lgkmcnt(3)
	v_mfma_f32_32x32x16_bf16 v[50:65], v[122:125], v[98:101], v[18:33]
	v_mfma_f32_32x32x16_bf16 v[66:81], v[110:113], v[86:89], v[66:81]
	s_waitcnt lgkmcnt(2)
	v_mfma_f32_32x32x16_bf16 v[50:65], v[156:159], v[86:89], v[50:65]
	v_mfma_f32_32x32x16_bf16 v[66:81], v[114:117], v[82:85], v[66:81]
	s_waitcnt lgkmcnt(1)
	v_mfma_f32_32x32x16_bf16 v[50:65], v[176:179], v[82:85], v[50:65]
	v_mfma_f32_32x32x16_bf16 v[66:81], v[118:121], v[90:93], v[66:81]
	ds_read_b128 v[114:117], v154 offset:57344
	ds_read_b128 v[110:113], v153 offset:57344
	ds_read_b128 v[118:121], v152 offset:57344
	ds_read_b128 v[122:125], v151 offset:57344
	s_waitcnt lgkmcnt(4)
	v_mfma_f32_32x32x16_bf16 v[50:65], v[180:183], v[90:93], v[50:65]
	s_nop 5
	v_max3_f32 v156, v66, v67, v68
	v_max3_f32 v156, v156, v69, v70
	v_max3_f32 v156, v156, v71, v72
	v_max3_f32 v156, v156, v73, v74
	v_max3_f32 v156, v156, v75, v76
	v_max3_f32 v156, v156, v77, v78
	v_max3_f32 v156, v156, v79, v80
	v_max3_f32 v157, v50, v51, v52
	v_max3_f32 v157, v157, v53, v54
	v_max3_f32 v157, v157, v55, v56
	v_max3_f32 v157, v157, v57, v58
	v_max3_f32 v157, v157, v59, v60
	v_max3_f32 v157, v157, v61, v62
	v_max3_f32 v157, v157, v63, v64
	v_max3_f32 v155, v156, v157, v81
	v_max_f32_e32 v155, v155, v65
	v_mov_b32_e32 v156, v155
	s_nop 1
	v_permlane32_swap_b32_e32 v155, v156
	v_max_f32_e32 v155, v155, v156
	v_cndmask_b32_e64 v156, v227, v228, s[36:37]
	v_cmp_gt_f32_e32 vcc, v155, v156
	s_cbranch_vccz .LBB0_142
	s_nop 0
	v_cndmask_b32_e32 v20, 0, v155, vcc
	v_exp_f32_e64 v22, -v20
	v_add_f32_e32 v150, v150, v20
	v_xor_b32_e32 v18, 0x80000000, v150
	v_pk_add_f32 v[66:67], v[66:67], v[20:21] op_sel_hi:[1,0] neg_lo:[0,1] neg_hi:[0,1]
	v_mul_f32_e32 v149, v149, v22
	v_pk_add_f32 v[50:51], v[50:51], v[20:21] op_sel_hi:[1,0] neg_lo:[0,1] neg_hi:[0,1]
	v_pk_add_f32 v[68:69], v[68:69], v[20:21] op_sel_hi:[1,0] neg_lo:[0,1] neg_hi:[0,1]
	v_pk_add_f32 v[52:53], v[52:53], v[20:21] op_sel_hi:[1,0] neg_lo:[0,1] neg_hi:[0,1]
	v_pk_add_f32 v[70:71], v[70:71], v[20:21] op_sel_hi:[1,0] neg_lo:[0,1] neg_hi:[0,1]
	v_pk_add_f32 v[54:55], v[54:55], v[20:21] op_sel_hi:[1,0] neg_lo:[0,1] neg_hi:[0,1]
	v_pk_add_f32 v[72:73], v[72:73], v[20:21] op_sel_hi:[1,0] neg_lo:[0,1] neg_hi:[0,1]
	v_pk_add_f32 v[56:57], v[56:57], v[20:21] op_sel_hi:[1,0] neg_lo:[0,1] neg_hi:[0,1]
	v_pk_add_f32 v[74:75], v[74:75], v[20:21] op_sel_hi:[1,0] neg_lo:[0,1] neg_hi:[0,1]
	v_pk_add_f32 v[58:59], v[58:59], v[20:21] op_sel_hi:[1,0] neg_lo:[0,1] neg_hi:[0,1]
	v_pk_add_f32 v[76:77], v[76:77], v[20:21] op_sel_hi:[1,0] neg_lo:[0,1] neg_hi:[0,1]
	v_pk_add_f32 v[60:61], v[60:61], v[20:21] op_sel_hi:[1,0] neg_lo:[0,1] neg_hi:[0,1]
	v_pk_add_f32 v[78:79], v[78:79], v[20:21] op_sel_hi:[1,0] neg_lo:[0,1] neg_hi:[0,1]
	v_pk_add_f32 v[62:63], v[62:63], v[20:21] op_sel_hi:[1,0] neg_lo:[0,1] neg_hi:[0,1]
	v_pk_mul_f32 v[48:49], v[48:49], v[22:23] op_sel_hi:[1,0]
	v_pk_mul_f32 v[46:47], v[46:47], v[22:23] op_sel_hi:[1,0]
	v_pk_mul_f32 v[44:45], v[44:45], v[22:23] op_sel_hi:[1,0]
	v_pk_mul_f32 v[42:43], v[42:43], v[22:23] op_sel_hi:[1,0]
	v_pk_mul_f32 v[40:41], v[40:41], v[22:23] op_sel_hi:[1,0]
	v_pk_mul_f32 v[38:39], v[38:39], v[22:23] op_sel_hi:[1,0]
	v_pk_mul_f32 v[36:37], v[36:37], v[22:23] op_sel_hi:[1,0]
	v_pk_mul_f32 v[34:35], v[34:35], v[22:23] op_sel_hi:[1,0]
	v_pk_mul_f32 v[16:17], v[16:17], v[22:23] op_sel_hi:[1,0]
	v_pk_mul_f32 v[14:15], v[14:15], v[22:23] op_sel_hi:[1,0]
	v_pk_mul_f32 v[12:13], v[12:13], v[22:23] op_sel_hi:[1,0]
	v_pk_mul_f32 v[10:11], v[10:11], v[22:23] op_sel_hi:[1,0]
	v_pk_mul_f32 v[8:9], v[8:9], v[22:23] op_sel_hi:[1,0]
	v_pk_mul_f32 v[6:7], v[6:7], v[22:23] op_sel_hi:[1,0]
	v_pk_mul_f32 v[4:5], v[4:5], v[22:23] op_sel_hi:[1,0]
	v_pk_mul_f32 v[2:3], v[2:3], v[22:23] op_sel_hi:[1,0]
	v_pk_add_f32 v[80:81], v[80:81], v[20:21] op_sel_hi:[1,0] neg_lo:[0,1] neg_hi:[0,1]
	v_pk_add_f32 v[64:65], v[64:65], v[20:21] op_sel_hi:[1,0] neg_lo:[0,1] neg_hi:[0,1]
	v_mov_b32_e32 v19, v18
	v_mov_b32_e32 v20, v18
	v_mov_b32_e32 v21, v18
	v_mov_b32_e32 v22, v18
	v_mov_b32_e32 v23, v18
	v_mov_b32_e32 v24, v18
	v_mov_b32_e32 v25, v18
	v_mov_b32_e32 v26, v18
	v_mov_b32_e32 v27, v18
	v_mov_b32_e32 v28, v18
	v_mov_b32_e32 v29, v18
	v_mov_b32_e32 v30, v18
	v_mov_b32_e32 v31, v18
	v_mov_b32_e32 v32, v18
	v_mov_b32_e32 v33, v18
	s_branch .LBB0_142

.LBB0_362:
	s_and_b32 s0, s43, 0x4000
	s_add_i32 s46, s0, 0
	v_add_u32_e32 v2, s46, v151
	v_add_u32_e32 v3, v2, v155
	s_waitcnt vmcnt(0)
	ds_write_b128 v3, v[114:117] offset:49152
	v_add3_u32 v3, v2, v153, v152
	v_add3_u32 v2, v2, v154, v152
	ds_write_b64 v3, v[118:119] offset:57344
	ds_write_b64 v2, v[120:121] offset:57344
	global_load_dwordx4 v[114:117], v[134:135], off
	global_load_dwordx4 v[118:121], v[132:133], off
	s_lshr_b32 s0, s44, 2
	v_lshrrev_b32_e32 v2, s0, v144
	v_and_b32_e32 v2, 1, v2
	v_cmp_eq_u32_e64 s[36:37], 1, v2
	v_bfe_u32 v2, v144, s0, 1
	s_andn2_b64 s[0:1], s[30:31], exec
	s_and_b64 s[38:39], s[30:31], exec
	v_cmp_ne_u32_e32 vcc, 0, v2
	s_or_b64 s[0:1], s[0:1], s[38:39]
	s_waitcnt lgkmcnt(0)
	s_barrier
	s_cbranch_vccz .LBB0_360
	v_add_u32_e32 v15, s46, v136
	s_mov_b32 s45, 0x7f800000
	v_add_u32_e32 v145, v15, v138
	ds_read_b128 v[2:5], v145 offset:49152
	v_add_u32_e32 v146, v15, v139
	ds_read_b128 v[6:9], v146 offset:49152
	v_add_u32_e32 v14, v15, v137
	ds_read_b128 v[10:13], v14 offset:49152
	v_add_u32_e32 v15, v15, v140
	ds_read_b128 v[122:125], v15 offset:49152
	ds_read_b128 v[156:159], v145 offset:53248
	ds_read_b128 v[160:163], v146 offset:53248
	ds_read_b128 v[164:167], v14 offset:53248
	ds_read_b128 v[168:171], v15 offset:53248
	s_waitcnt lgkmcnt(7)
	v_mfma_f32_32x32x16_bf16 v[64:79], v[2:5], v[110:113], v[48:63]
	s_cmp_lg_u64 vcc, -1
	s_cselect_b64 s[38:39], -1, 0
	s_cmp_eq_u64 vcc, -1
	s_cselect_b64 s[40:41], -1, 0
	s_or_b64 vcc, s[40:41], s[36:37]
	s_waitcnt lgkmcnt(3)
	v_mfma_f32_32x32x16_bf16 v[80:95], v[156:159], v[110:113], v[48:63]
	v_mfma_f32_32x32x16_bf16 v[64:79], v[6:9], v[106:109], v[64:79]
	s_waitcnt lgkmcnt(2)
	v_mfma_f32_32x32x16_bf16 v[80:95], v[160:163], v[106:109], v[80:95]
	v_mfma_f32_32x32x16_bf16 v[64:79], v[10:13], v[102:105], v[64:79]
	s_waitcnt lgkmcnt(1)
	v_mfma_f32_32x32x16_bf16 v[80:95], v[164:167], v[102:105], v[80:95]
	v_mfma_f32_32x32x16_bf16 v[64:79], v[122:125], v[98:101], v[64:79]
	ds_read_b128 v[6:9], v145 offset:57344
	ds_read_b128 v[2:5], v146 offset:57344
	ds_read_b128 v[10:13], v14 offset:57344
	ds_read_b128 v[122:125], v15 offset:57344
	s_waitcnt lgkmcnt(4)
	v_mfma_f32_32x32x16_bf16 v[80:95], v[168:171], v[98:101], v[80:95]
	s_nop 5
	v_max3_f32 v148, v64, v65, v66
	v_max3_f32 v148, v148, v67, v68
	v_max3_f32 v148, v148, v69, v70
	v_max3_f32 v148, v148, v71, v72
	v_max3_f32 v148, v148, v73, v74
	v_max3_f32 v148, v148, v75, v76
	v_max3_f32 v148, v148, v77, v78
	v_max3_f32 v149, v80, v81, v82
	v_max3_f32 v149, v149, v83, v84
	v_max3_f32 v149, v149, v85, v86
	v_max3_f32 v149, v149, v87, v88
	v_max3_f32 v149, v149, v89, v90
	v_max3_f32 v149, v149, v91, v92
	v_max3_f32 v149, v149, v93, v94
	v_max3_f32 v147, v148, v149, v79
	v_max_f32_e32 v147, v147, v95
	v_cndmask_b32_e32 v147, v225, v147, vcc
	v_mov_b32_e32 v148, v147
	s_nop 1
	v_permlane32_swap_b32_e32 v147, v148
	v_max_f32_e32 v147, v147, v148
	v_cndmask_b32_e64 v148, v227, v228, s[30:31]
	v_cmp_gt_f32_e32 vcc, v147, v148
	s_cbranch_vccz .LBB0_365
	s_nop 0
	v_cndmask_b32_e32 v50, 0, v147, vcc
	v_exp_f32_e64 v52, -v50
	v_add_f32_e32 v143, v143, v50
	v_xor_b32_e32 v48, 0x80000000, v143
	v_pk_add_f32 v[64:65], v[64:65], v[50:51] op_sel_hi:[1,0] neg_lo:[0,1] neg_hi:[0,1]
	v_mul_f32_e32 v0, v0, v52
	v_pk_add_f32 v[80:81], v[80:81], v[50:51] op_sel_hi:[1,0] neg_lo:[0,1] neg_hi:[0,1]
	v_pk_add_f32 v[66:67], v[66:67], v[50:51] op_sel_hi:[1,0] neg_lo:[0,1] neg_hi:[0,1]
	v_pk_add_f32 v[82:83], v[82:83], v[50:51] op_sel_hi:[1,0] neg_lo:[0,1] neg_hi:[0,1]
	v_pk_add_f32 v[68:69], v[68:69], v[50:51] op_sel_hi:[1,0] neg_lo:[0,1] neg_hi:[0,1]
	v_pk_add_f32 v[84:85], v[84:85], v[50:51] op_sel_hi:[1,0] neg_lo:[0,1] neg_hi:[0,1]
	v_pk_add_f32 v[70:71], v[70:71], v[50:51] op_sel_hi:[1,0] neg_lo:[0,1] neg_hi:[0,1]
	v_pk_add_f32 v[86:87], v[86:87], v[50:51] op_sel_hi:[1,0] neg_lo:[0,1] neg_hi:[0,1]
	v_pk_add_f32 v[72:73], v[72:73], v[50:51] op_sel_hi:[1,0] neg_lo:[0,1] neg_hi:[0,1]
	v_pk_add_f32 v[88:89], v[88:89], v[50:51] op_sel_hi:[1,0] neg_lo:[0,1] neg_hi:[0,1]
	v_pk_add_f32 v[74:75], v[74:75], v[50:51] op_sel_hi:[1,0] neg_lo:[0,1] neg_hi:[0,1]
	v_pk_add_f32 v[90:91], v[90:91], v[50:51] op_sel_hi:[1,0] neg_lo:[0,1] neg_hi:[0,1]
	v_pk_add_f32 v[76:77], v[76:77], v[50:51] op_sel_hi:[1,0] neg_lo:[0,1] neg_hi:[0,1]
	v_pk_add_f32 v[92:93], v[92:93], v[50:51] op_sel_hi:[1,0] neg_lo:[0,1] neg_hi:[0,1]
	v_pk_mul_f32 v[46:47], v[46:47], v[52:53] op_sel_hi:[1,0]
	v_pk_mul_f32 v[44:45], v[44:45], v[52:53] op_sel_hi:[1,0]
	v_pk_mul_f32 v[42:43], v[42:43], v[52:53] op_sel_hi:[1,0]
	v_pk_mul_f32 v[40:41], v[40:41], v[52:53] op_sel_hi:[1,0]
	v_pk_mul_f32 v[38:39], v[38:39], v[52:53] op_sel_hi:[1,0]
	v_pk_mul_f32 v[36:37], v[36:37], v[52:53] op_sel_hi:[1,0]
	v_pk_mul_f32 v[34:35], v[34:35], v[52:53] op_sel_hi:[1,0]
	v_pk_mul_f32 v[32:33], v[32:33], v[52:53] op_sel_hi:[1,0]
	v_pk_mul_f32 v[30:31], v[30:31], v[52:53] op_sel_hi:[1,0]
	v_pk_mul_f32 v[28:29], v[28:29], v[52:53] op_sel_hi:[1,0]
	v_pk_mul_f32 v[26:27], v[26:27], v[52:53] op_sel_hi:[1,0]
	v_pk_mul_f32 v[24:25], v[24:25], v[52:53] op_sel_hi:[1,0]
	v_pk_mul_f32 v[22:23], v[22:23], v[52:53] op_sel_hi:[1,0]
	v_pk_mul_f32 v[20:21], v[20:21], v[52:53] op_sel_hi:[1,0]
	v_pk_mul_f32 v[18:19], v[18:19], v[52:53] op_sel_hi:[1,0]
	v_pk_mul_f32 v[16:17], v[16:17], v[52:53] op_sel_hi:[1,0]
	v_pk_add_f32 v[78:79], v[78:79], v[50:51] op_sel_hi:[1,0] neg_lo:[0,1] neg_hi:[0,1]
	v_pk_add_f32 v[94:95], v[94:95], v[50:51] op_sel_hi:[1,0] neg_lo:[0,1] neg_hi:[0,1]
	v_mov_b32_e32 v49, v48
	v_mov_b32_e32 v50, v48
	v_mov_b32_e32 v51, v48
	v_mov_b32_e32 v52, v48
	v_mov_b32_e32 v53, v48
	v_mov_b32_e32 v54, v48
	v_mov_b32_e32 v55, v48
	v_mov_b32_e32 v56, v48
	v_mov_b32_e32 v57, v48
	v_mov_b32_e32 v58, v48
	v_mov_b32_e32 v59, v48
	v_mov_b32_e32 v60, v48
	v_mov_b32_e32 v61, v48
	v_mov_b32_e32 v62, v48
	v_mov_b32_e32 v63, v48
.LBB0_365:
	v_exp_f32_e32 v149, v64
	v_exp_f32_e32 v148, v80
	v_exp_f32_e32 v65, v65
	v_exp_f32_e32 v64, v81
	v_exp_f32_e32 v157, v66
	v_exp_f32_e32 v156, v82
	v_exp_f32_e32 v67, v67
	v_exp_f32_e32 v66, v83
	v_exp_f32_e32 v83, v68
	v_exp_f32_e32 v82, v84
	v_pk_add_f32 v[80:81], v[64:65], v[148:149]
	v_exp_f32_e32 v159, v69
	v_exp_f32_e32 v158, v85
	v_pk_add_f32 v[80:81], v[156:157], v[80:81]
	v_exp_f32_e32 v85, v70
	v_exp_f32_e32 v84, v86
	v_pk_add_f32 v[80:81], v[66:67], v[80:81]
	v_exp_f32_e32 v161, v71
	v_exp_f32_e32 v160, v87
	v_exp_f32_e32 v87, v72
	v_exp_f32_e32 v86, v88
	v_pk_add_f32 v[68:69], v[82:83], v[80:81]
	v_exp_f32_e32 v163, v73
	v_exp_f32_e32 v162, v89
	v_pk_add_f32 v[68:69], v[158:159], v[68:69]
	v_exp_f32_e32 v89, v74
	v_exp_f32_e32 v88, v90
	v_pk_add_f32 v[68:69], v[84:85], v[68:69]
	v_exp_f32_e32 v165, v75
	v_exp_f32_e32 v164, v91
	v_pk_add_f32 v[68:69], v[160:161], v[68:69]
	v_exp_f32_e32 v91, v76
	v_exp_f32_e32 v90, v92
	v_pk_add_f32 v[68:69], v[86:87], v[68:69]
	v_exp_f32_e32 v167, v77
	v_exp_f32_e32 v166, v93
	v_pk_add_f32 v[68:69], v[162:163], v[68:69]
	v_exp_f32_e32 v93, v78
	v_exp_f32_e32 v92, v94
	v_pk_add_f32 v[68:69], v[88:89], v[68:69]
	v_exp_f32_e32 v169, v79
	v_exp_f32_e32 v168, v95
	v_pk_add_f32 v[68:69], v[164:165], v[68:69]
	v_cvt_pk_bf16_f32 v72, v149, v65
	v_pk_add_f32 v[68:69], v[90:91], v[68:69]
	v_cvt_pk_bf16_f32 v73, v157, v67
	v_pk_add_f32 v[68:69], v[166:167], v[68:69]
	v_cvt_pk_bf16_f32 v74, v83, v159
	v_pk_add_f32 v[68:69], v[92:93], v[68:69]
	v_cvt_pk_bf16_f32 v75, v85, v161
	v_pk_add_f32 v[68:69], v[168:169], v[68:69]
	v_cvt_pk_bf16_f32 v76, v87, v163
	v_add_f32_e32 v80, v68, v69
	v_cvt_pk_bf16_f32 v77, v89, v165
	v_cvt_pk_bf16_f32 v78, v91, v167
	v_cvt_pk_bf16_f32 v79, v93, v169
	v_cvt_pk_bf16_f32 v68, v148, v64
	v_cvt_pk_bf16_f32 v69, v156, v66
	v_cvt_pk_bf16_f32 v70, v82, v158
	v_cvt_pk_bf16_f32 v71, v84, v160
	v_cvt_pk_bf16_f32 v64, v86, v162
	v_cvt_pk_bf16_f32 v65, v88, v164
	v_cvt_pk_bf16_f32 v66, v90, v166
	s_andn2_b64 vcc, exec, s[38:39]
	v_cvt_pk_bf16_f32 v67, v92, v168
	s_cbranch_vccnz .LBB0_367
	v_cndmask_b32_e64 v80, 0, v80, s[36:37]
	v_cndmask_b32_e64 v72, 0, v72, s[36:37]
	v_cndmask_b32_e64 v73, 0, v73, s[36:37]
	v_cndmask_b32_e64 v74, 0, v74, s[36:37]
	v_cndmask_b32_e64 v75, 0, v75, s[36:37]
	v_cndmask_b32_e64 v76, 0, v76, s[36:37]
	v_cndmask_b32_e64 v77, 0, v77, s[36:37]
	v_cndmask_b32_e64 v78, 0, v78, s[36:37]
	v_cndmask_b32_e64 v79, 0, v79, s[36:37]
	v_cndmask_b32_e64 v68, 0, v68, s[36:37]
	v_cndmask_b32_e64 v69, 0, v69, s[36:37]
	v_cndmask_b32_e64 v70, 0, v70, s[36:37]
	v_cndmask_b32_e64 v71, 0, v71, s[36:37]
	v_cndmask_b32_e64 v64, 0, v64, s[36:37]
	v_cndmask_b32_e64 v65, 0, v65, s[36:37]
	v_cndmask_b32_e64 v66, 0, v66, s[36:37]
	v_cndmask_b32_e64 v67, 0, v67, s[36:37]

.LBB0_372:
	s_nop 7
	v_max3_f32 v164, v80, v81, v82
	v_max3_f32 v164, v164, v83, v84
	v_max3_f32 v164, v164, v85, v86
	v_max3_f32 v164, v164, v87, v88
	v_max3_f32 v164, v164, v89, v90
	v_max3_f32 v164, v164, v91, v92
	v_max3_f32 v164, v164, v93, v94
	v_max3_f32 v165, v64, v65, v66
	v_max3_f32 v165, v165, v67, v68
	v_max3_f32 v165, v165, v69, v70
	v_max3_f32 v165, v165, v71, v72
	v_max3_f32 v165, v165, v73, v74
	v_max3_f32 v165, v165, v75, v76
	v_max3_f32 v165, v165, v77, v78
	v_max3_f32 v163, v164, v165, v95
	v_max_f32_e32 v163, v163, v79
	v_mov_b32_e32 v164, v163
	s_nop 1
	v_permlane32_swap_b32_e32 v163, v164
	v_max_f32_e32 v163, v163, v164
	v_cndmask_b32_e64 v164, v227, v228, s[30:31]
	v_cmp_gt_f32_e32 vcc, v163, v164
	s_cbranch_vccz .LBB0_374
	s_nop 0
	v_cndmask_b32_e32 v50, 0, v163, vcc
	v_exp_f32_e64 v52, -v50
	v_add_f32_e32 v143, v143, v50
	v_xor_b32_e32 v48, 0x80000000, v143
	v_pk_add_f32 v[80:81], v[80:81], v[50:51] op_sel_hi:[1,0] neg_lo:[0,1] neg_hi:[0,1]
	v_mul_f32_e32 v0, v0, v52
	v_pk_add_f32 v[64:65], v[64:65], v[50:51] op_sel_hi:[1,0] neg_lo:[0,1] neg_hi:[0,1]
	v_pk_add_f32 v[82:83], v[82:83], v[50:51] op_sel_hi:[1,0] neg_lo:[0,1] neg_hi:[0,1]
	v_pk_add_f32 v[66:67], v[66:67], v[50:51] op_sel_hi:[1,0] neg_lo:[0,1] neg_hi:[0,1]
	v_pk_add_f32 v[84:85], v[84:85], v[50:51] op_sel_hi:[1,0] neg_lo:[0,1] neg_hi:[0,1]
	v_pk_add_f32 v[68:69], v[68:69], v[50:51] op_sel_hi:[1,0] neg_lo:[0,1] neg_hi:[0,1]
	v_pk_add_f32 v[86:87], v[86:87], v[50:51] op_sel_hi:[1,0] neg_lo:[0,1] neg_hi:[0,1]
	v_pk_add_f32 v[70:71], v[70:71], v[50:51] op_sel_hi:[1,0] neg_lo:[0,1] neg_hi:[0,1]
	v_pk_add_f32 v[88:89], v[88:89], v[50:51] op_sel_hi:[1,0] neg_lo:[0,1] neg_hi:[0,1]
	v_pk_add_f32 v[72:73], v[72:73], v[50:51] op_sel_hi:[1,0] neg_lo:[0,1] neg_hi:[0,1]
	v_pk_add_f32 v[90:91], v[90:91], v[50:51] op_sel_hi:[1,0] neg_lo:[0,1] neg_hi:[0,1]
	v_pk_add_f32 v[74:75], v[74:75], v[50:51] op_sel_hi:[1,0] neg_lo:[0,1] neg_hi:[0,1]
	v_pk_add_f32 v[92:93], v[92:93], v[50:51] op_sel_hi:[1,0] neg_lo:[0,1] neg_hi:[0,1]
	v_pk_add_f32 v[76:77], v[76:77], v[50:51] op_sel_hi:[1,0] neg_lo:[0,1] neg_hi:[0,1]
	v_pk_mul_f32 v[46:47], v[46:47], v[52:53] op_sel_hi:[1,0]
	v_pk_mul_f32 v[44:45], v[44:45], v[52:53] op_sel_hi:[1,0]
	v_pk_mul_f32 v[42:43], v[42:43], v[52:53] op_sel_hi:[1,0]
	v_pk_mul_f32 v[40:41], v[40:41], v[52:53] op_sel_hi:[1,0]
	v_pk_mul_f32 v[38:39], v[38:39], v[52:53] op_sel_hi:[1,0]
	v_pk_mul_f32 v[36:37], v[36:37], v[52:53] op_sel_hi:[1,0]
	v_pk_mul_f32 v[34:35], v[34:35], v[52:53] op_sel_hi:[1,0]
	v_pk_mul_f32 v[32:33], v[32:33], v[52:53] op_sel_hi:[1,0]
	v_pk_mul_f32 v[30:31], v[30:31], v[52:53] op_sel_hi:[1,0]
	v_pk_mul_f32 v[28:29], v[28:29], v[52:53] op_sel_hi:[1,0]
	v_pk_mul_f32 v[26:27], v[26:27], v[52:53] op_sel_hi:[1,0]
	v_pk_mul_f32 v[24:25], v[24:25], v[52:53] op_sel_hi:[1,0]
	v_pk_mul_f32 v[22:23], v[22:23], v[52:53] op_sel_hi:[1,0]
	v_pk_mul_f32 v[20:21], v[20:21], v[52:53] op_sel_hi:[1,0]
	v_pk_mul_f32 v[18:19], v[18:19], v[52:53] op_sel_hi:[1,0]
	v_pk_mul_f32 v[16:17], v[16:17], v[52:53] op_sel_hi:[1,0]
	v_pk_add_f32 v[94:95], v[94:95], v[50:51] op_sel_hi:[1,0] neg_lo:[0,1] neg_hi:[0,1]
	v_pk_add_f32 v[78:79], v[78:79], v[50:51] op_sel_hi:[1,0] neg_lo:[0,1] neg_hi:[0,1]
	v_mov_b32_e32 v49, v48
	v_mov_b32_e32 v50, v48
	v_mov_b32_e32 v51, v48
	v_mov_b32_e32 v52, v48
	v_mov_b32_e32 v53, v48
	v_mov_b32_e32 v54, v48
	v_mov_b32_e32 v55, v48
	v_mov_b32_e32 v56, v48
	v_mov_b32_e32 v57, v48
	v_mov_b32_e32 v58, v48
	v_mov_b32_e32 v59, v48
	v_mov_b32_e32 v60, v48
	v_mov_b32_e32 v61, v48
	v_mov_b32_e32 v62, v48
	v_mov_b32_e32 v63, v48

.LBB0_378:
	s_nop 7
	v_max3_f32 v162, v80, v81, v82
	v_max3_f32 v162, v162, v83, v84
	v_max3_f32 v162, v162, v85, v86
	v_max3_f32 v162, v162, v87, v88
	v_max3_f32 v162, v162, v89, v90
	v_max3_f32 v162, v162, v91, v92
	v_max3_f32 v162, v162, v93, v94
	v_max3_f32 v163, v64, v65, v66
	v_max3_f32 v163, v163, v67, v68
	v_max3_f32 v163, v163, v69, v70
	v_max3_f32 v163, v163, v71, v72
	v_max3_f32 v163, v163, v73, v74
	v_max3_f32 v163, v163, v75, v76
	v_max3_f32 v163, v163, v77, v78
	v_max3_f32 v161, v162, v163, v95
	v_max_f32_e32 v161, v161, v79
	v_mov_b32_e32 v162, v161
	s_nop 1
	v_permlane32_swap_b32_e32 v161, v162
	v_max_f32_e32 v161, v161, v162
	v_cndmask_b32_e64 v162, v227, v228, s[30:31]
	v_cmp_gt_f32_e32 vcc, v161, v162
	s_cbranch_vccz .LBB0_380
	s_nop 0
	v_cndmask_b32_e32 v50, 0, v161, vcc
	v_exp_f32_e64 v52, -v50
	v_add_f32_e32 v143, v143, v50
	v_xor_b32_e32 v48, 0x80000000, v143
	v_pk_add_f32 v[80:81], v[80:81], v[50:51] op_sel_hi:[1,0] neg_lo:[0,1] neg_hi:[0,1]
	v_mul_f32_e32 v0, v0, v52
	v_pk_add_f32 v[64:65], v[64:65], v[50:51] op_sel_hi:[1,0] neg_lo:[0,1] neg_hi:[0,1]
	v_pk_add_f32 v[82:83], v[82:83], v[50:51] op_sel_hi:[1,0] neg_lo:[0,1] neg_hi:[0,1]
	v_pk_add_f32 v[66:67], v[66:67], v[50:51] op_sel_hi:[1,0] neg_lo:[0,1] neg_hi:[0,1]
	v_pk_add_f32 v[84:85], v[84:85], v[50:51] op_sel_hi:[1,0] neg_lo:[0,1] neg_hi:[0,1]
	v_pk_add_f32 v[68:69], v[68:69], v[50:51] op_sel_hi:[1,0] neg_lo:[0,1] neg_hi:[0,1]
	v_pk_add_f32 v[86:87], v[86:87], v[50:51] op_sel_hi:[1,0] neg_lo:[0,1] neg_hi:[0,1]
	v_pk_add_f32 v[70:71], v[70:71], v[50:51] op_sel_hi:[1,0] neg_lo:[0,1] neg_hi:[0,1]
	v_pk_add_f32 v[88:89], v[88:89], v[50:51] op_sel_hi:[1,0] neg_lo:[0,1] neg_hi:[0,1]
	v_pk_add_f32 v[72:73], v[72:73], v[50:51] op_sel_hi:[1,0] neg_lo:[0,1] neg_hi:[0,1]
	v_pk_add_f32 v[90:91], v[90:91], v[50:51] op_sel_hi:[1,0] neg_lo:[0,1] neg_hi:[0,1]
	v_pk_add_f32 v[74:75], v[74:75], v[50:51] op_sel_hi:[1,0] neg_lo:[0,1] neg_hi:[0,1]
	v_pk_add_f32 v[92:93], v[92:93], v[50:51] op_sel_hi:[1,0] neg_lo:[0,1] neg_hi:[0,1]
	v_pk_add_f32 v[76:77], v[76:77], v[50:51] op_sel_hi:[1,0] neg_lo:[0,1] neg_hi:[0,1]
	v_pk_mul_f32 v[46:47], v[46:47], v[52:53] op_sel_hi:[1,0]
	v_pk_mul_f32 v[44:45], v[44:45], v[52:53] op_sel_hi:[1,0]
	v_pk_mul_f32 v[42:43], v[42:43], v[52:53] op_sel_hi:[1,0]
	v_pk_mul_f32 v[40:41], v[40:41], v[52:53] op_sel_hi:[1,0]
	v_pk_mul_f32 v[38:39], v[38:39], v[52:53] op_sel_hi:[1,0]
	v_pk_mul_f32 v[36:37], v[36:37], v[52:53] op_sel_hi:[1,0]
	v_pk_mul_f32 v[34:35], v[34:35], v[52:53] op_sel_hi:[1,0]
	v_pk_mul_f32 v[32:33], v[32:33], v[52:53] op_sel_hi:[1,0]
	v_pk_mul_f32 v[30:31], v[30:31], v[52:53] op_sel_hi:[1,0]
	v_pk_mul_f32 v[28:29], v[28:29], v[52:53] op_sel_hi:[1,0]
	v_pk_mul_f32 v[26:27], v[26:27], v[52:53] op_sel_hi:[1,0]
	v_pk_mul_f32 v[24:25], v[24:25], v[52:53] op_sel_hi:[1,0]
	v_pk_mul_f32 v[22:23], v[22:23], v[52:53] op_sel_hi:[1,0]
	v_pk_mul_f32 v[20:21], v[20:21], v[52:53] op_sel_hi:[1,0]
	v_pk_mul_f32 v[18:19], v[18:19], v[52:53] op_sel_hi:[1,0]
	v_pk_mul_f32 v[16:17], v[16:17], v[52:53] op_sel_hi:[1,0]
	v_pk_add_f32 v[94:95], v[94:95], v[50:51] op_sel_hi:[1,0] neg_lo:[0,1] neg_hi:[0,1]
	v_pk_add_f32 v[78:79], v[78:79], v[50:51] op_sel_hi:[1,0] neg_lo:[0,1] neg_hi:[0,1]
	v_mov_b32_e32 v49, v48
	v_mov_b32_e32 v50, v48
	v_mov_b32_e32 v51, v48
	v_mov_b32_e32 v52, v48
	v_mov_b32_e32 v53, v48
	v_mov_b32_e32 v54, v48
	v_mov_b32_e32 v55, v48
	v_mov_b32_e32 v56, v48
	v_mov_b32_e32 v57, v48
	v_mov_b32_e32 v58, v48
	v_mov_b32_e32 v59, v48
	v_mov_b32_e32 v60, v48
	v_mov_b32_e32 v61, v48
	v_mov_b32_e32 v62, v48
	v_mov_b32_e32 v63, v48

.LBB0_384:
	s_nop 7
	v_max3_f32 v154, v80, v81, v82
	v_max3_f32 v154, v154, v83, v84
	v_max3_f32 v154, v154, v85, v86
	v_max3_f32 v154, v154, v87, v88
	v_max3_f32 v154, v154, v89, v90
	v_max3_f32 v154, v154, v91, v92
	v_max3_f32 v154, v154, v93, v94
	v_max3_f32 v156, v64, v65, v66
	v_max3_f32 v156, v156, v67, v68
	v_max3_f32 v156, v156, v69, v70
	v_max3_f32 v156, v156, v71, v72
	v_max3_f32 v156, v156, v73, v74
	v_max3_f32 v156, v156, v75, v76
	v_max3_f32 v156, v156, v77, v78
	v_max3_f32 v153, v154, v156, v95
	v_max_f32_e32 v153, v153, v79
	v_mov_b32_e32 v154, v153
	s_nop 1
	v_permlane32_swap_b32_e32 v153, v154
	v_max_f32_e32 v153, v153, v154
	v_cndmask_b32_e64 v154, v227, v228, s[30:31]
	v_cmp_gt_f32_e32 vcc, v153, v154
	s_cbranch_vccz .LBB0_386
	s_nop 0
	v_cndmask_b32_e32 v50, 0, v153, vcc
	v_exp_f32_e64 v52, -v50
	v_add_f32_e32 v48, v143, v50
	v_xor_b32_e32 v48, 0x80000000, v48
	v_pk_add_f32 v[80:81], v[80:81], v[50:51] op_sel_hi:[1,0] neg_lo:[0,1] neg_hi:[0,1]
	v_mul_f32_e32 v0, v0, v52
	v_pk_add_f32 v[64:65], v[64:65], v[50:51] op_sel_hi:[1,0] neg_lo:[0,1] neg_hi:[0,1]
	v_pk_add_f32 v[82:83], v[82:83], v[50:51] op_sel_hi:[1,0] neg_lo:[0,1] neg_hi:[0,1]
	v_pk_add_f32 v[66:67], v[66:67], v[50:51] op_sel_hi:[1,0] neg_lo:[0,1] neg_hi:[0,1]
	v_pk_add_f32 v[84:85], v[84:85], v[50:51] op_sel_hi:[1,0] neg_lo:[0,1] neg_hi:[0,1]
	v_pk_add_f32 v[68:69], v[68:69], v[50:51] op_sel_hi:[1,0] neg_lo:[0,1] neg_hi:[0,1]
	v_pk_add_f32 v[86:87], v[86:87], v[50:51] op_sel_hi:[1,0] neg_lo:[0,1] neg_hi:[0,1]
	v_pk_add_f32 v[70:71], v[70:71], v[50:51] op_sel_hi:[1,0] neg_lo:[0,1] neg_hi:[0,1]
	v_pk_add_f32 v[88:89], v[88:89], v[50:51] op_sel_hi:[1,0] neg_lo:[0,1] neg_hi:[0,1]
	v_pk_add_f32 v[72:73], v[72:73], v[50:51] op_sel_hi:[1,0] neg_lo:[0,1] neg_hi:[0,1]
	v_pk_add_f32 v[90:91], v[90:91], v[50:51] op_sel_hi:[1,0] neg_lo:[0,1] neg_hi:[0,1]
	v_pk_add_f32 v[74:75], v[74:75], v[50:51] op_sel_hi:[1,0] neg_lo:[0,1] neg_hi:[0,1]
	v_pk_add_f32 v[92:93], v[92:93], v[50:51] op_sel_hi:[1,0] neg_lo:[0,1] neg_hi:[0,1]
	v_pk_add_f32 v[76:77], v[76:77], v[50:51] op_sel_hi:[1,0] neg_lo:[0,1] neg_hi:[0,1]
	v_pk_mul_f32 v[46:47], v[46:47], v[52:53] op_sel_hi:[1,0]
	v_pk_mul_f32 v[44:45], v[44:45], v[52:53] op_sel_hi:[1,0]
	v_pk_mul_f32 v[42:43], v[42:43], v[52:53] op_sel_hi:[1,0]
	v_pk_mul_f32 v[40:41], v[40:41], v[52:53] op_sel_hi:[1,0]
	v_pk_mul_f32 v[38:39], v[38:39], v[52:53] op_sel_hi:[1,0]
	v_pk_mul_f32 v[36:37], v[36:37], v[52:53] op_sel_hi:[1,0]
	v_pk_mul_f32 v[34:35], v[34:35], v[52:53] op_sel_hi:[1,0]
	v_pk_mul_f32 v[32:33], v[32:33], v[52:53] op_sel_hi:[1,0]
	v_pk_mul_f32 v[30:31], v[30:31], v[52:53] op_sel_hi:[1,0]
	v_pk_mul_f32 v[28:29], v[28:29], v[52:53] op_sel_hi:[1,0]
	v_pk_mul_f32 v[26:27], v[26:27], v[52:53] op_sel_hi:[1,0]
	v_pk_mul_f32 v[24:25], v[24:25], v[52:53] op_sel_hi:[1,0]
	v_pk_mul_f32 v[22:23], v[22:23], v[52:53] op_sel_hi:[1,0]
	v_pk_mul_f32 v[20:21], v[20:21], v[52:53] op_sel_hi:[1,0]
	v_pk_mul_f32 v[18:19], v[18:19], v[52:53] op_sel_hi:[1,0]
	v_pk_mul_f32 v[16:17], v[16:17], v[52:53] op_sel_hi:[1,0]
	v_pk_add_f32 v[94:95], v[94:95], v[50:51] op_sel_hi:[1,0] neg_lo:[0,1] neg_hi:[0,1]
	v_pk_add_f32 v[78:79], v[78:79], v[50:51] op_sel_hi:[1,0] neg_lo:[0,1] neg_hi:[0,1]
	v_mov_b32_e32 v49, v48
	v_mov_b32_e32 v50, v48
	v_mov_b32_e32 v51, v48
	v_mov_b32_e32 v52, v48
	v_mov_b32_e32 v53, v48
	v_mov_b32_e32 v54, v48
	v_mov_b32_e32 v55, v48
	v_mov_b32_e32 v56, v48
	v_mov_b32_e32 v57, v48
	v_mov_b32_e32 v58, v48
	v_mov_b32_e32 v59, v48
	v_mov_b32_e32 v60, v48
	v_mov_b32_e32 v61, v48
	v_mov_b32_e32 v62, v48
	v_mov_b32_e32 v63, v48
.LBB0_386:
	v_exp_f32_e32 v173, v92
	v_exp_f32_e32 v175, v94
	v_exp_f32_e32 v172, v76
	v_exp_f32_e32 v92, v77
	v_exp_f32_e32 v174, v78
	v_exp_f32_e32 v94, v79
	ds_read_b128 v[76:79], v14 offset:61440
	v_exp_f32_e32 v157, v80
	v_exp_f32_e32 v159, v81
	v_exp_f32_e32 v161, v82
	v_exp_f32_e32 v163, v83
	v_exp_f32_e32 v165, v84
	v_exp_f32_e32 v85, v85
	v_exp_f32_e32 v167, v86
	v_exp_f32_e32 v87, v87
	v_exp_f32_e32 v156, v64
	v_exp_f32_e32 v158, v65
	v_exp_f32_e32 v160, v66
	v_exp_f32_e32 v162, v67
	v_cvt_pk_bf16_f32 v64, v157, v159
	v_cvt_pk_bf16_f32 v65, v161, v163
	v_cvt_pk_bf16_f32 v66, v165, v85
	v_cvt_pk_bf16_f32 v67, v167, v87
	ds_read_b128 v[80:83], v15 offset:61440
	v_exp_f32_e32 v169, v88
	v_mfma_f32_32x32x16_bf16 v[32:47], v[10:13], v[64:67], v[32:47]
	v_exp_f32_e32 v89, v89
	v_exp_f32_e32 v171, v90
	v_exp_f32_e32 v91, v91
	v_exp_f32_e32 v93, v93
	v_exp_f32_e32 v95, v95
	v_exp_f32_e32 v164, v68
	s_waitcnt lgkmcnt(1)
	v_mfma_f32_32x32x16_bf16 v[16:31], v[76:79], v[64:67], v[16:31]
	v_exp_f32_e32 v84, v69
	v_pk_add_f32 v[14:15], v[158:159], v[156:157]
	v_exp_f32_e32 v166, v70
	v_cvt_pk_bf16_f32 v10, v169, v89
	v_cvt_pk_bf16_f32 v11, v171, v91
	v_cvt_pk_bf16_f32 v12, v173, v93
	v_cvt_pk_bf16_f32 v13, v175, v95
	v_pk_add_f32 v[14:15], v[160:161], v[14:15]
	ds_read_b128 v[64:67], v128 offset:61440
	v_exp_f32_e32 v86, v71
	v_mfma_f32_32x32x16_bf16 v[32:47], v[114:117], v[10:13], v[32:47]
	v_add_f32_e64 v14, v162, v14
	v_add_f32_e64 v15, v163, v15
	v_exp_f32_e32 v168, v72
	v_pk_add_f32 v[14:15], v[164:165], v[14:15]
	v_exp_f32_e32 v88, v73
	v_exp_f32_e32 v170, v74
	v_cvt_pk_bf16_f32 v68, v156, v158
	v_cvt_pk_bf16_f32 v69, v160, v162
	s_waitcnt lgkmcnt(1)
	v_mfma_f32_32x32x16_bf16 v[16:31], v[80:83], v[10:13], v[16:31]
	v_add_f32_e64 v10, v84, v14
	v_add_f32_e64 v11, v85, v15
	v_cvt_pk_bf16_f32 v70, v164, v84
	v_add_f32_e64 v10, v166, v10
	v_add_f32_e64 v11, v167, v11
	v_cvt_pk_bf16_f32 v71, v166, v86
	v_pk_add_f32 v[10:11], v[86:87], v[10:11]
	v_exp_f32_e32 v90, v75
	v_pk_add_f32 v[10:11], v[168:169], v[10:11]
	v_mfma_f32_32x32x16_bf16 v[32:47], v[122:125], v[68:71], v[32:47]
	v_add_f32_e64 v10, v88, v10
	v_add_f32_e64 v11, v89, v11
	v_cvt_pk_bf16_f32 v72, v168, v88
	v_add_f32_e64 v14, v170, v10
	v_add_f32_e64 v15, v171, v11
	ds_read_b128 v[10:13], v129 offset:61440
	v_cvt_pk_bf16_f32 v73, v170, v90
	v_cvt_pk_bf16_f32 v74, v172, v92
	v_cvt_pk_bf16_f32 v75, v174, v94
	s_waitcnt lgkmcnt(1)
	v_mfma_f32_32x32x16_bf16 v[16:31], v[64:67], v[68:71], v[16:31]
	v_add_f32_e64 v14, v90, v14
	v_add_f32_e64 v15, v91, v15
	v_cmp_lt_f32_e32 vcc, s24, v153
	v_add_f32_e64 v14, v172, v14
	v_add_f32_e64 v15, v173, v15
	s_or_b64 s[30:31], s[30:31], vcc
	v_pk_add_f32 v[14:15], v[92:93], v[14:15]
	s_nop 0
	v_pk_add_f32 v[14:15], v[174:175], v[14:15]
	v_mfma_f32_32x32x16_bf16 v[32:47], v[118:121], v[72:75], v[32:47]
	v_add_f32_e64 v14, v94, v14
	v_add_f32_e64 v15, v95, v15
	v_add_f32_e32 v14, v14, v15
	v_add_f32_e32 v0, v0, v14
	s_waitcnt lgkmcnt(0)
	v_mfma_f32_32x32x16_bf16 v[16:31], v[10:13], v[72:75], v[16:31]

.LBB0_390:
	s_nop 7
	v_max3_f32 v87, v64, v65, v66
	v_max3_f32 v87, v87, v67, v68
	v_max3_f32 v87, v87, v69, v70
	v_max3_f32 v87, v87, v71, v72
	v_max3_f32 v87, v87, v73, v74
	v_max3_f32 v87, v87, v75, v76
	v_max3_f32 v87, v87, v77, v78
	v_max3_f32 v88, v48, v49, v50
	v_max3_f32 v88, v88, v51, v52
	v_max3_f32 v88, v88, v53, v54
	v_max3_f32 v88, v88, v55, v56
	v_max3_f32 v88, v88, v57, v58
	v_max3_f32 v88, v88, v59, v60
	v_max3_f32 v88, v88, v61, v62
	v_max3_f32 v86, v87, v88, v79
	v_max_f32_e32 v86, v86, v63
	v_mov_b32_e32 v87, v86
	s_nop 1
	v_permlane32_swap_b32_e32 v86, v87
	v_max_f32_e32 v86, v86, v87
	v_cndmask_b32_e64 v87, v227, v228, s[30:31]
	v_cmp_gt_f32_e32 vcc, v86, v87
	s_cbranch_vccz .LBB0_198
	s_nop 0
	v_cndmask_b32_e32 v86, 0, v86, vcc
	v_exp_f32_e64 v88, -v86
	v_pk_add_f32 v[64:65], v[64:65], v[86:87] op_sel_hi:[1,0] neg_lo:[0,1] neg_hi:[0,1]
	v_pk_add_f32 v[48:49], v[48:49], v[86:87] op_sel_hi:[1,0] neg_lo:[0,1] neg_hi:[0,1]
	v_pk_add_f32 v[66:67], v[66:67], v[86:87] op_sel_hi:[1,0] neg_lo:[0,1] neg_hi:[0,1]
	v_mul_f32_e32 v0, v0, v88
	v_pk_add_f32 v[50:51], v[50:51], v[86:87] op_sel_hi:[1,0] neg_lo:[0,1] neg_hi:[0,1]
	v_pk_add_f32 v[68:69], v[68:69], v[86:87] op_sel_hi:[1,0] neg_lo:[0,1] neg_hi:[0,1]
	v_pk_add_f32 v[52:53], v[52:53], v[86:87] op_sel_hi:[1,0] neg_lo:[0,1] neg_hi:[0,1]
	v_pk_add_f32 v[70:71], v[70:71], v[86:87] op_sel_hi:[1,0] neg_lo:[0,1] neg_hi:[0,1]
	v_pk_add_f32 v[54:55], v[54:55], v[86:87] op_sel_hi:[1,0] neg_lo:[0,1] neg_hi:[0,1]
	v_pk_add_f32 v[72:73], v[72:73], v[86:87] op_sel_hi:[1,0] neg_lo:[0,1] neg_hi:[0,1]
	v_pk_add_f32 v[56:57], v[56:57], v[86:87] op_sel_hi:[1,0] neg_lo:[0,1] neg_hi:[0,1]
	v_pk_add_f32 v[74:75], v[74:75], v[86:87] op_sel_hi:[1,0] neg_lo:[0,1] neg_hi:[0,1]
	v_pk_add_f32 v[58:59], v[58:59], v[86:87] op_sel_hi:[1,0] neg_lo:[0,1] neg_hi:[0,1]
	v_pk_add_f32 v[76:77], v[76:77], v[86:87] op_sel_hi:[1,0] neg_lo:[0,1] neg_hi:[0,1]
	v_pk_add_f32 v[60:61], v[60:61], v[86:87] op_sel_hi:[1,0] neg_lo:[0,1] neg_hi:[0,1]
	v_pk_mul_f32 v[46:47], v[46:47], v[88:89] op_sel_hi:[1,0]
	v_pk_mul_f32 v[44:45], v[44:45], v[88:89] op_sel_hi:[1,0]
	v_pk_mul_f32 v[42:43], v[42:43], v[88:89] op_sel_hi:[1,0]
	v_pk_mul_f32 v[40:41], v[40:41], v[88:89] op_sel_hi:[1,0]
	v_pk_mul_f32 v[38:39], v[38:39], v[88:89] op_sel_hi:[1,0]
	v_pk_mul_f32 v[36:37], v[36:37], v[88:89] op_sel_hi:[1,0]
	v_pk_mul_f32 v[34:35], v[34:35], v[88:89] op_sel_hi:[1,0]
	v_pk_mul_f32 v[32:33], v[32:33], v[88:89] op_sel_hi:[1,0]
	v_pk_mul_f32 v[30:31], v[30:31], v[88:89] op_sel_hi:[1,0]
	v_pk_mul_f32 v[28:29], v[28:29], v[88:89] op_sel_hi:[1,0]
	v_pk_mul_f32 v[26:27], v[26:27], v[88:89] op_sel_hi:[1,0]
	v_pk_mul_f32 v[24:25], v[24:25], v[88:89] op_sel_hi:[1,0]
	v_pk_mul_f32 v[22:23], v[22:23], v[88:89] op_sel_hi:[1,0]
	v_pk_mul_f32 v[20:21], v[20:21], v[88:89] op_sel_hi:[1,0]
	v_pk_mul_f32 v[18:19], v[18:19], v[88:89] op_sel_hi:[1,0]
	v_pk_mul_f32 v[16:17], v[16:17], v[88:89] op_sel_hi:[1,0]
	v_pk_add_f32 v[78:79], v[78:79], v[86:87] op_sel_hi:[1,0] neg_lo:[0,1] neg_hi:[0,1]
	v_pk_add_f32 v[62:63], v[62:63], v[86:87] op_sel_hi:[1,0] neg_lo:[0,1] neg_hi:[0,1]
	s_branch .LBB0_198
